# g2 + EpiUq/EpiUkv: per-thread 16B load pulls the tile's 8KiB rms statistics panel into L1 before the dependent per-row statistics loads
# baseline (speedup 1.0000x reference)
; #define GAS __attribute__((address_space(1)))
; __device__ __forceinline__ unsigned cvtpk(float lo, float hi) { return __builtin_bit_cast(unsigned, __builtin_convertvector(f32x2_cv{lo, hi}, bf16x2_cv)); }
; __device__ __forceinline__ bf16_t f2bf(float f) { return (bf16_t)(cvtpk(f, 0.f) & 0xffffu); }
; __device__ __forceinline__ float rstd_from_ssq(const float* __restrict__ ssq, int row) {
;     const f32x4 a = *(const GAS f32x4*)(ssq + (size_t)row * 8), c = *(const GAS f32x4*)(ssq + (size_t)row * 8 + 4);
;     return rsqrtf(((a[0] + a[1]) + (a[2] + a[3]) + (c[0] + c[1]) + (c[2] + c[3])) * (1.f / 512.f) + RMS_EPS);
; }
;     __device__ __forceinline__ void operator()(const f32x4 (&acc)[2][2][4][2], int brow, int bcol, int wr, int wc, int fr, int fq) const {
;     ...
;                     const int row = brow + ai * 128 + wr * 64 + m * 16 + fq * 4 + j, sq = row & 4095;
;                     const float rs = rstd_from_ssq(ssq, row);
;                     if (bcol < 1024) {
; #pragma unroll
;                         for (int bj = 0; bj < 2; ++bj)
;                             *(GAS unsigned*)(qm + ((size_t)(b * 8 + (bcol >> 7) + bj) * S + sq) * 192 + wc * 32 + 2 * fr) = cvtpk(acc[ai][bj][m][0][j] * rs, acc[ai][bj][m][1][j] * rs);
;                     } else {
;                         const int i = (wc & 1) * 16 + fr;
;                         const float2 cs = r64[sq * 32 + i];
; #pragma unroll
;                         for (int bj = 0; bj < 2; ++bj) {
;                             const int head = ((bcol - 1024) >> 8) * 4 + bj * 2 + (wc >> 1);
;                             const float x1 = acc[ai][bj][m][0][j] * rs, x2 = acc[ai][bj][m][1][j] * rs;
;                             GAS bf16_t* p = (GAS bf16_t*)(qm + ((size_t)(b * 8 + head) * S + sq) * 192 + 128);
;                             p[i] = f2bf(x1 * cs.x - x2 * cs.y); p[32 + i] = f2bf(x2 * cs.x + x1 * cs.y);
;                         }
.LBB0_751:
	s_or_b64 exec, exec, s[12:13]
	v_lshlrev_b32_e32 v1, 2, v1
	v_add_u32_e32 v133, s42, v133
	v_or_b32_e32 v134, v133, v1
	v_ashrrev_i32_e32 v135, 31, v134
	v_and_b32_e32 v243, 0xffffff00, v134
	v_lshlrev_b32_e32 v243, 5, v243
	v_lshl_add_u32 v242, v0, 4, v243
	v_mov_b32_e32 v243, 0
	v_lshl_add_u64 v[242:243], s[46:47], 0, v[242:243]
	global_load_dwordx4 v[250:253], v[242:243], off
	v_or_b32_e32 v240, 1, v134
	v_ashrrev_i32_e32 v241, 31, v240
	v_lshlrev_b64 v[240:241], 5, v[240:241]
	v_lshl_add_u64 v[240:241], s[46:47], 0, v[240:241]
	global_load_dwordx4 v[208:211], v[240:241], off offset:16
	global_load_dwordx4 v[224:227], v[240:241], off
	v_or_b32_e32 v240, 2, v134
	v_ashrrev_i32_e32 v241, 31, v240
	v_lshlrev_b64 v[240:241], 5, v[240:241]
	v_lshl_add_u64 v[240:241], s[46:47], 0, v[240:241]
	global_load_dwordx4 v[212:215], v[240:241], off offset:16
	global_load_dwordx4 v[228:231], v[240:241], off
	v_or_b32_e32 v240, 3, v134
	v_ashrrev_i32_e32 v241, 31, v240
	v_lshlrev_b64 v[240:241], 5, v[240:241]
	v_lshl_add_u64 v[240:241], s[46:47], 0, v[240:241]
	global_load_dwordx4 v[216:219], v[240:241], off offset:16
	global_load_dwordx4 v[232:235], v[240:241], off
	v_or_b32_e32 v240, 16, v134
	v_ashrrev_i32_e32 v241, 31, v240
	v_lshlrev_b64 v[240:241], 5, v[240:241]
	v_lshl_add_u64 v[240:241], s[46:47], 0, v[240:241]
	global_load_dwordx4 v[220:223], v[240:241], off offset:16
	global_load_dwordx4 v[236:239], v[240:241], off
	s_waitcnt vmcnt(6)
	v_add_f32_e32 v242, v225, v224
	v_add_f32_e32 v243, v226, v227
	v_add_f32_e32 v244, v210, v211
	v_add_f32_e32 v245, v208, v209
	v_add_f32_e32 v242, v242, v243
	v_add_f32_e32 v242, v242, v245
	v_add_f32_e32 v242, v244, v242
	v_fmamk_f32 v242, v242, 0x3b000000, v201
	v_cmp_gt_f32_e32 vcc, s33, v242
	v_mul_f32_e32 v243, 0x4b800000, v242
	s_nop 0
	v_cndmask_b32_e32 v242, v242, v243, vcc
	v_rsq_f32_e32 v242, v242
	s_nop 0
	v_mul_f32_e32 v243, 0x45800000, v242
	v_cndmask_b32_e32 v154, v242, v243, vcc
	s_waitcnt vmcnt(4)
	v_add_f32_e32 v242, v229, v228
	v_add_f32_e32 v243, v230, v231
	v_add_f32_e32 v244, v214, v215
	v_add_f32_e32 v245, v212, v213
	v_add_f32_e32 v242, v242, v243
	v_add_f32_e32 v242, v242, v245
	v_add_f32_e32 v242, v244, v242
	v_fmamk_f32 v242, v242, 0x3b000000, v201
	v_cmp_gt_f32_e32 vcc, s33, v242
	v_mul_f32_e32 v243, 0x4b800000, v242
	s_nop 0
	v_cndmask_b32_e32 v242, v242, v243, vcc
	v_rsq_f32_e32 v242, v242
	s_nop 0
	v_mul_f32_e32 v243, 0x45800000, v242
	v_cndmask_b32_e32 v155, v242, v243, vcc
	s_waitcnt vmcnt(2)
	v_add_f32_e32 v242, v233, v232
	v_add_f32_e32 v243, v234, v235
	v_add_f32_e32 v244, v218, v219
	v_add_f32_e32 v245, v216, v217
	v_add_f32_e32 v242, v242, v243
	v_add_f32_e32 v242, v242, v245
	v_add_f32_e32 v242, v244, v242
	v_fmamk_f32 v242, v242, 0x3b000000, v201
	v_cmp_gt_f32_e32 vcc, s33, v242
	v_mul_f32_e32 v243, 0x4b800000, v242
	s_nop 0
	v_cndmask_b32_e32 v242, v242, v243, vcc
	v_rsq_f32_e32 v242, v242
	s_nop 0
	v_mul_f32_e32 v243, 0x45800000, v242
	v_cndmask_b32_e32 v156, v242, v243, vcc
	s_waitcnt vmcnt(0)
	v_add_f32_e32 v242, v237, v236
	v_add_f32_e32 v243, v238, v239
	v_add_f32_e32 v244, v222, v223
	v_add_f32_e32 v245, v220, v221
	v_add_f32_e32 v242, v242, v243
	v_add_f32_e32 v242, v242, v245
	v_add_f32_e32 v242, v244, v242
	v_fmamk_f32 v242, v242, 0x3b000000, v201
	v_cmp_gt_f32_e32 vcc, s33, v242
	v_mul_f32_e32 v243, 0x4b800000, v242
	s_nop 0
	v_cndmask_b32_e32 v242, v242, v243, vcc
	v_rsq_f32_e32 v242, v242
	s_nop 0
	v_mul_f32_e32 v243, 0x45800000, v242
	v_cndmask_b32_e32 v157, v242, v243, vcc
	v_or_b32_e32 v240, 17, v134
	v_ashrrev_i32_e32 v241, 31, v240
	v_lshlrev_b64 v[240:241], 5, v[240:241]
	v_lshl_add_u64 v[240:241], s[46:47], 0, v[240:241]
	global_load_dwordx4 v[208:211], v[240:241], off offset:16
	global_load_dwordx4 v[224:227], v[240:241], off
	v_or_b32_e32 v240, 18, v134
	v_ashrrev_i32_e32 v241, 31, v240
	v_lshlrev_b64 v[240:241], 5, v[240:241]
	v_lshl_add_u64 v[240:241], s[46:47], 0, v[240:241]
	global_load_dwordx4 v[212:215], v[240:241], off offset:16
	global_load_dwordx4 v[228:231], v[240:241], off
	v_or_b32_e32 v240, 19, v134
	v_ashrrev_i32_e32 v241, 31, v240
	v_lshlrev_b64 v[240:241], 5, v[240:241]
	v_lshl_add_u64 v[240:241], s[46:47], 0, v[240:241]
	global_load_dwordx4 v[216:219], v[240:241], off offset:16
	global_load_dwordx4 v[232:235], v[240:241], off
	v_or_b32_e32 v240, 32, v134
	v_ashrrev_i32_e32 v241, 31, v240
	v_lshlrev_b64 v[240:241], 5, v[240:241]
	v_lshl_add_u64 v[240:241], s[46:47], 0, v[240:241]
	global_load_dwordx4 v[220:223], v[240:241], off offset:16
	global_load_dwordx4 v[236:239], v[240:241], off
	s_waitcnt vmcnt(6)
	v_add_f32_e32 v242, v225, v224
	v_add_f32_e32 v243, v226, v227
	v_add_f32_e32 v244, v210, v211
	v_add_f32_e32 v245, v208, v209
	v_add_f32_e32 v242, v242, v243
	v_add_f32_e32 v242, v242, v245
	v_add_f32_e32 v242, v244, v242
	v_fmamk_f32 v242, v242, 0x3b000000, v201
	v_cmp_gt_f32_e32 vcc, s33, v242
	v_mul_f32_e32 v243, 0x4b800000, v242
	s_nop 0
	v_cndmask_b32_e32 v242, v242, v243, vcc
	v_rsq_f32_e32 v242, v242
	s_nop 0
	v_mul_f32_e32 v243, 0x45800000, v242
	v_cndmask_b32_e32 v158, v242, v243, vcc
	s_waitcnt vmcnt(4)
	v_add_f32_e32 v242, v229, v228
	v_add_f32_e32 v243, v230, v231
	v_add_f32_e32 v244, v214, v215
	v_add_f32_e32 v245, v212, v213
	v_add_f32_e32 v242, v242, v243
	v_add_f32_e32 v242, v242, v245
	v_add_f32_e32 v242, v244, v242
	v_fmamk_f32 v242, v242, 0x3b000000, v201
	v_cmp_gt_f32_e32 vcc, s33, v242
	v_mul_f32_e32 v243, 0x4b800000, v242
	s_nop 0
	v_cndmask_b32_e32 v242, v242, v243, vcc
	v_rsq_f32_e32 v242, v242
	s_nop 0
	v_mul_f32_e32 v243, 0x45800000, v242
	v_cndmask_b32_e32 v159, v242, v243, vcc
	s_waitcnt vmcnt(2)
; #define GAS __attribute__((address_space(1)))
; __device__ __forceinline__ float rstd_from_ssq(const float* __restrict__ ssq, int row) {
;     const f32x4 a = *(const GAS f32x4*)(ssq + (size_t)row * 8), c = *(const GAS f32x4*)(ssq + (size_t)row * 8 + 4);
;     return rsqrtf(((a[0] + a[1]) + (a[2] + a[3]) + (c[0] + c[1]) + (c[2] + c[3])) * (1.f / 512.f) + RMS_EPS);
; }
;     __device__ __forceinline__ void operator()(const f32x4 (&acc)[2][2][4][2], int brow, int bcol, int wr, int wc, int fr, int fq) const {
;     ...
;                     const int row = brow + ai * 128 + wr * 64 + m * 16 + fq * 4 + j, sq = row & 4095;
;                     const float rs = rstd_from_ssq(ssq, row);
	v_add_f32_e32 v242, v233, v232
	v_add_f32_e32 v243, v234, v235
	v_add_f32_e32 v244, v218, v219
	v_add_f32_e32 v245, v216, v217
	v_add_f32_e32 v242, v242, v243
	v_add_f32_e32 v242, v242, v245
	v_add_f32_e32 v242, v244, v242
	v_fmamk_f32 v242, v242, 0x3b000000, v201
	v_cmp_gt_f32_e32 vcc, s33, v242
	v_mul_f32_e32 v243, 0x4b800000, v242
	s_nop 0
	v_cndmask_b32_e32 v242, v242, v243, vcc
	v_rsq_f32_e32 v242, v242
	s_nop 0
	v_mul_f32_e32 v243, 0x45800000, v242
	v_cndmask_b32_e32 v160, v242, v243, vcc
	s_waitcnt vmcnt(0)
	v_add_f32_e32 v242, v237, v236
	v_add_f32_e32 v243, v238, v239
	v_add_f32_e32 v244, v222, v223
	v_add_f32_e32 v245, v220, v221
	v_add_f32_e32 v242, v242, v243
	v_add_f32_e32 v242, v242, v245
	v_add_f32_e32 v242, v244, v242
	v_fmamk_f32 v242, v242, 0x3b000000, v201
	v_cmp_gt_f32_e32 vcc, s33, v242
	v_mul_f32_e32 v243, 0x4b800000, v242
	s_nop 0
	v_cndmask_b32_e32 v242, v242, v243, vcc
	v_rsq_f32_e32 v242, v242
	s_nop 0
	v_mul_f32_e32 v243, 0x45800000, v242
	v_cndmask_b32_e32 v161, v242, v243, vcc
	v_or_b32_e32 v240, 33, v134
	v_ashrrev_i32_e32 v241, 31, v240
	v_lshlrev_b64 v[240:241], 5, v[240:241]
	v_lshl_add_u64 v[240:241], s[46:47], 0, v[240:241]
	global_load_dwordx4 v[208:211], v[240:241], off offset:16
	global_load_dwordx4 v[224:227], v[240:241], off
	v_or_b32_e32 v240, 34, v134
	v_ashrrev_i32_e32 v241, 31, v240
	v_lshlrev_b64 v[240:241], 5, v[240:241]
	v_lshl_add_u64 v[240:241], s[46:47], 0, v[240:241]
	global_load_dwordx4 v[212:215], v[240:241], off offset:16
	global_load_dwordx4 v[228:231], v[240:241], off
	v_or_b32_e32 v240, 35, v134
	v_ashrrev_i32_e32 v241, 31, v240
	v_lshlrev_b64 v[240:241], 5, v[240:241]
	v_lshl_add_u64 v[240:241], s[46:47], 0, v[240:241]
	global_load_dwordx4 v[216:219], v[240:241], off offset:16
	global_load_dwordx4 v[232:235], v[240:241], off
	v_or_b32_e32 v240, 48, v134
	v_ashrrev_i32_e32 v241, 31, v240
	v_lshlrev_b64 v[240:241], 5, v[240:241]
	v_lshl_add_u64 v[240:241], s[46:47], 0, v[240:241]
	global_load_dwordx4 v[220:223], v[240:241], off offset:16
	global_load_dwordx4 v[236:239], v[240:241], off
	s_waitcnt vmcnt(6)
	v_add_f32_e32 v242, v225, v224
	v_add_f32_e32 v243, v226, v227
	v_add_f32_e32 v244, v210, v211
	v_add_f32_e32 v245, v208, v209
	v_add_f32_e32 v242, v242, v243
	v_add_f32_e32 v242, v242, v245
	v_add_f32_e32 v242, v244, v242
	v_fmamk_f32 v242, v242, 0x3b000000, v201
	v_cmp_gt_f32_e32 vcc, s33, v242
	v_mul_f32_e32 v243, 0x4b800000, v242
	s_nop 0
	v_cndmask_b32_e32 v242, v242, v243, vcc
	v_rsq_f32_e32 v242, v242
	s_nop 0
	v_mul_f32_e32 v243, 0x45800000, v242
	v_cndmask_b32_e32 v162, v242, v243, vcc
	s_waitcnt vmcnt(4)
	v_add_f32_e32 v242, v229, v228
	v_add_f32_e32 v243, v230, v231
	v_add_f32_e32 v244, v214, v215
	v_add_f32_e32 v245, v212, v213
	v_add_f32_e32 v242, v242, v243
	v_add_f32_e32 v242, v242, v245
	v_add_f32_e32 v242, v244, v242
	v_fmamk_f32 v242, v242, 0x3b000000, v201
	v_cmp_gt_f32_e32 vcc, s33, v242
	v_mul_f32_e32 v243, 0x4b800000, v242
	s_nop 0
	v_cndmask_b32_e32 v242, v242, v243, vcc
	v_rsq_f32_e32 v242, v242
	s_nop 0
	v_mul_f32_e32 v243, 0x45800000, v242
	v_cndmask_b32_e32 v163, v242, v243, vcc
	s_waitcnt vmcnt(2)
	v_add_f32_e32 v242, v233, v232
	v_add_f32_e32 v243, v234, v235
	v_add_f32_e32 v244, v218, v219
	v_add_f32_e32 v245, v216, v217
	v_add_f32_e32 v242, v242, v243
	v_add_f32_e32 v242, v242, v245
	v_add_f32_e32 v242, v244, v242
	v_fmamk_f32 v242, v242, 0x3b000000, v201
	v_cmp_gt_f32_e32 vcc, s33, v242
	v_mul_f32_e32 v243, 0x4b800000, v242
	s_nop 0
	v_cndmask_b32_e32 v242, v242, v243, vcc
	v_rsq_f32_e32 v242, v242
	s_nop 0
	v_mul_f32_e32 v243, 0x45800000, v242
	v_cndmask_b32_e32 v164, v242, v243, vcc
	s_waitcnt vmcnt(0)
	v_add_f32_e32 v242, v237, v236
	v_add_f32_e32 v243, v238, v239
	v_add_f32_e32 v244, v222, v223
	v_add_f32_e32 v245, v220, v221
	v_add_f32_e32 v242, v242, v243
	v_add_f32_e32 v242, v242, v245
	v_add_f32_e32 v242, v244, v242
	v_fmamk_f32 v242, v242, 0x3b000000, v201
	v_cmp_gt_f32_e32 vcc, s33, v242
	v_mul_f32_e32 v243, 0x4b800000, v242
	s_nop 0
	v_cndmask_b32_e32 v242, v242, v243, vcc
	v_rsq_f32_e32 v242, v242
	s_nop 0
	v_mul_f32_e32 v243, 0x45800000, v242
	v_cndmask_b32_e32 v165, v242, v243, vcc
	v_or_b32_e32 v240, 49, v134
	v_ashrrev_i32_e32 v241, 31, v240
	v_lshlrev_b64 v[240:241], 5, v[240:241]
	v_lshl_add_u64 v[240:241], s[46:47], 0, v[240:241]
	global_load_dwordx4 v[208:211], v[240:241], off offset:16
	global_load_dwordx4 v[224:227], v[240:241], off
	v_or_b32_e32 v240, 50, v134
	v_ashrrev_i32_e32 v241, 31, v240
	v_lshlrev_b64 v[240:241], 5, v[240:241]
	v_lshl_add_u64 v[240:241], s[46:47], 0, v[240:241]
	global_load_dwordx4 v[212:215], v[240:241], off offset:16
	global_load_dwordx4 v[228:231], v[240:241], off
	v_or_b32_e32 v240, 51, v134
	v_ashrrev_i32_e32 v241, 31, v240
	v_lshlrev_b64 v[240:241], 5, v[240:241]
	v_lshl_add_u64 v[240:241], s[46:47], 0, v[240:241]
	global_load_dwordx4 v[216:219], v[240:241], off offset:16
	global_load_dwordx4 v[232:235], v[240:241], off
	v_add_u32_e32 v240, 0x80, v134
	v_ashrrev_i32_e32 v241, 31, v240
	v_lshlrev_b64 v[240:241], 5, v[240:241]
	v_lshl_add_u64 v[240:241], s[46:47], 0, v[240:241]
	global_load_dwordx4 v[220:223], v[240:241], off offset:16
	global_load_dwordx4 v[236:239], v[240:241], off
	s_waitcnt vmcnt(6)
	v_add_f32_e32 v242, v225, v224
	v_add_f32_e32 v243, v226, v227
	v_add_f32_e32 v244, v210, v211
	v_add_f32_e32 v245, v208, v209
	v_add_f32_e32 v242, v242, v243
	v_add_f32_e32 v242, v242, v245
	v_add_f32_e32 v242, v244, v242
	v_fmamk_f32 v242, v242, 0x3b000000, v201
	v_cmp_gt_f32_e32 vcc, s33, v242
	v_mul_f32_e32 v243, 0x4b800000, v242
	s_nop 0
	v_cndmask_b32_e32 v242, v242, v243, vcc
	v_rsq_f32_e32 v242, v242
	s_nop 0
	v_mul_f32_e32 v243, 0x45800000, v242
	v_cndmask_b32_e32 v166, v242, v243, vcc
	s_waitcnt vmcnt(4)
; #define GAS __attribute__((address_space(1)))
; __device__ __forceinline__ float rstd_from_ssq(const float* __restrict__ ssq, int row) {
;     const f32x4 a = *(const GAS f32x4*)(ssq + (size_t)row * 8), c = *(const GAS f32x4*)(ssq + (size_t)row * 8 + 4);
;     return rsqrtf(((a[0] + a[1]) + (a[2] + a[3]) + (c[0] + c[1]) + (c[2] + c[3])) * (1.f / 512.f) + RMS_EPS);
; }
;     __device__ __forceinline__ void operator()(const f32x4 (&acc)[2][2][4][2], int brow, int bcol, int wr, int wc, int fr, int fq) const {
;     ...
;                     const int row = brow + ai * 128 + wr * 64 + m * 16 + fq * 4 + j, sq = row & 4095;
;                     const float rs = rstd_from_ssq(ssq, row);
	v_add_f32_e32 v242, v229, v228
	v_add_f32_e32 v243, v230, v231
	v_add_f32_e32 v244, v214, v215
	v_add_f32_e32 v245, v212, v213
	v_add_f32_e32 v242, v242, v243
	v_add_f32_e32 v242, v242, v245
	v_add_f32_e32 v242, v244, v242
	v_fmamk_f32 v242, v242, 0x3b000000, v201
	v_cmp_gt_f32_e32 vcc, s33, v242
	v_mul_f32_e32 v243, 0x4b800000, v242
	s_nop 0
	v_cndmask_b32_e32 v242, v242, v243, vcc
	v_rsq_f32_e32 v242, v242
	s_nop 0
	v_mul_f32_e32 v243, 0x45800000, v242
	v_cndmask_b32_e32 v167, v242, v243, vcc
	s_waitcnt vmcnt(2)
	v_add_f32_e32 v242, v233, v232
	v_add_f32_e32 v243, v234, v235
	v_add_f32_e32 v244, v218, v219
	v_add_f32_e32 v245, v216, v217
	v_add_f32_e32 v242, v242, v243
	v_add_f32_e32 v242, v242, v245
	v_add_f32_e32 v242, v244, v242
	v_fmamk_f32 v242, v242, 0x3b000000, v201
	v_cmp_gt_f32_e32 vcc, s33, v242
	v_mul_f32_e32 v243, 0x4b800000, v242
	s_nop 0
	v_cndmask_b32_e32 v242, v242, v243, vcc
	v_rsq_f32_e32 v242, v242
	s_nop 0
	v_mul_f32_e32 v243, 0x45800000, v242
	v_cndmask_b32_e32 v168, v242, v243, vcc
	s_waitcnt vmcnt(0)
	v_add_f32_e32 v242, v237, v236
	v_add_f32_e32 v243, v238, v239
	v_add_f32_e32 v244, v222, v223
	v_add_f32_e32 v245, v220, v221
	v_add_f32_e32 v242, v242, v243
	v_add_f32_e32 v242, v242, v245
	v_add_f32_e32 v242, v244, v242
	v_fmamk_f32 v242, v242, 0x3b000000, v201
	v_cmp_gt_f32_e32 vcc, s33, v242
	v_mul_f32_e32 v243, 0x4b800000, v242
	s_nop 0
	v_cndmask_b32_e32 v242, v242, v243, vcc
	v_rsq_f32_e32 v242, v242
	s_nop 0
	v_mul_f32_e32 v243, 0x45800000, v242
	v_cndmask_b32_e32 v169, v242, v243, vcc
	v_add_u32_e32 v240, 0x81, v134
	v_ashrrev_i32_e32 v241, 31, v240
	v_lshlrev_b64 v[240:241], 5, v[240:241]
	v_lshl_add_u64 v[240:241], s[46:47], 0, v[240:241]
	global_load_dwordx4 v[208:211], v[240:241], off offset:16
	global_load_dwordx4 v[224:227], v[240:241], off
	v_add_u32_e32 v240, 0x82, v134
	v_ashrrev_i32_e32 v241, 31, v240
	v_lshlrev_b64 v[240:241], 5, v[240:241]
	v_lshl_add_u64 v[240:241], s[46:47], 0, v[240:241]
	global_load_dwordx4 v[212:215], v[240:241], off offset:16
	global_load_dwordx4 v[228:231], v[240:241], off
	v_add_u32_e32 v240, 0x83, v134
	v_ashrrev_i32_e32 v241, 31, v240
	v_lshlrev_b64 v[240:241], 5, v[240:241]
	v_lshl_add_u64 v[240:241], s[46:47], 0, v[240:241]
	global_load_dwordx4 v[216:219], v[240:241], off offset:16
	global_load_dwordx4 v[232:235], v[240:241], off
	v_add_u32_e32 v240, 0x90, v134
	v_ashrrev_i32_e32 v241, 31, v240
	v_lshlrev_b64 v[240:241], 5, v[240:241]
	v_lshl_add_u64 v[240:241], s[46:47], 0, v[240:241]
	global_load_dwordx4 v[220:223], v[240:241], off offset:16
	global_load_dwordx4 v[236:239], v[240:241], off
	s_waitcnt vmcnt(6)
	v_add_f32_e32 v242, v225, v224
	v_add_f32_e32 v243, v226, v227
	v_add_f32_e32 v244, v210, v211
	v_add_f32_e32 v245, v208, v209
	v_add_f32_e32 v242, v242, v243
	v_add_f32_e32 v242, v242, v245
	v_add_f32_e32 v242, v244, v242
	v_fmamk_f32 v242, v242, 0x3b000000, v201
	v_cmp_gt_f32_e32 vcc, s33, v242
	v_mul_f32_e32 v243, 0x4b800000, v242
	s_nop 0
	v_cndmask_b32_e32 v242, v242, v243, vcc
	v_rsq_f32_e32 v242, v242
	s_nop 0
	v_mul_f32_e32 v243, 0x45800000, v242
	v_cndmask_b32_e32 v170, v242, v243, vcc
	s_waitcnt vmcnt(4)
	v_add_f32_e32 v242, v229, v228
	v_add_f32_e32 v243, v230, v231
	v_add_f32_e32 v244, v214, v215
	v_add_f32_e32 v245, v212, v213
	v_add_f32_e32 v242, v242, v243
	v_add_f32_e32 v242, v242, v245
	v_add_f32_e32 v242, v244, v242
	v_fmamk_f32 v242, v242, 0x3b000000, v201
	v_cmp_gt_f32_e32 vcc, s33, v242
	v_mul_f32_e32 v243, 0x4b800000, v242
	s_nop 0
	v_cndmask_b32_e32 v242, v242, v243, vcc
	v_rsq_f32_e32 v242, v242
	s_nop 0
	v_mul_f32_e32 v243, 0x45800000, v242
	v_cndmask_b32_e32 v171, v242, v243, vcc
	s_waitcnt vmcnt(2)
	v_add_f32_e32 v242, v233, v232
	v_add_f32_e32 v243, v234, v235
	v_add_f32_e32 v244, v218, v219
	v_add_f32_e32 v245, v216, v217
	v_add_f32_e32 v242, v242, v243
	v_add_f32_e32 v242, v242, v245
	v_add_f32_e32 v242, v244, v242
	v_fmamk_f32 v242, v242, 0x3b000000, v201
	v_cmp_gt_f32_e32 vcc, s33, v242
	v_mul_f32_e32 v243, 0x4b800000, v242
	s_nop 0
	v_cndmask_b32_e32 v242, v242, v243, vcc
	v_rsq_f32_e32 v242, v242
	s_nop 0
	v_mul_f32_e32 v243, 0x45800000, v242
	v_cndmask_b32_e32 v172, v242, v243, vcc
	s_waitcnt vmcnt(0)
	v_add_f32_e32 v242, v237, v236
	v_add_f32_e32 v243, v238, v239
	v_add_f32_e32 v244, v222, v223
	v_add_f32_e32 v245, v220, v221
	v_add_f32_e32 v242, v242, v243
	v_add_f32_e32 v242, v242, v245
	v_add_f32_e32 v242, v244, v242
	v_fmamk_f32 v242, v242, 0x3b000000, v201
	v_cmp_gt_f32_e32 vcc, s33, v242
	v_mul_f32_e32 v243, 0x4b800000, v242
	s_nop 0
	v_cndmask_b32_e32 v242, v242, v243, vcc
	v_rsq_f32_e32 v242, v242
	s_nop 0
	v_mul_f32_e32 v243, 0x45800000, v242
	v_cndmask_b32_e32 v173, v242, v243, vcc
	v_add_u32_e32 v240, 0x91, v134
	v_ashrrev_i32_e32 v241, 31, v240
	v_lshlrev_b64 v[240:241], 5, v[240:241]
	v_lshl_add_u64 v[240:241], s[46:47], 0, v[240:241]
	global_load_dwordx4 v[208:211], v[240:241], off offset:16
	global_load_dwordx4 v[224:227], v[240:241], off
	v_add_u32_e32 v240, 0x92, v134
	v_ashrrev_i32_e32 v241, 31, v240
	v_lshlrev_b64 v[240:241], 5, v[240:241]
	v_lshl_add_u64 v[240:241], s[46:47], 0, v[240:241]
	global_load_dwordx4 v[212:215], v[240:241], off offset:16
	global_load_dwordx4 v[228:231], v[240:241], off
	v_add_u32_e32 v240, 0x93, v134
	v_ashrrev_i32_e32 v241, 31, v240
	v_lshlrev_b64 v[240:241], 5, v[240:241]
	v_lshl_add_u64 v[240:241], s[46:47], 0, v[240:241]
	global_load_dwordx4 v[216:219], v[240:241], off offset:16
	global_load_dwordx4 v[232:235], v[240:241], off
	v_add_u32_e32 v240, 0xa0, v134
	v_ashrrev_i32_e32 v241, 31, v240
	v_lshlrev_b64 v[240:241], 5, v[240:241]
	v_lshl_add_u64 v[240:241], s[46:47], 0, v[240:241]
	global_load_dwordx4 v[220:223], v[240:241], off offset:16
	global_load_dwordx4 v[236:239], v[240:241], off
	s_waitcnt vmcnt(6)
; #define GAS __attribute__((address_space(1)))
; __device__ __forceinline__ float rstd_from_ssq(const float* __restrict__ ssq, int row) {
;     const f32x4 a = *(const GAS f32x4*)(ssq + (size_t)row * 8), c = *(const GAS f32x4*)(ssq + (size_t)row * 8 + 4);
;     return rsqrtf(((a[0] + a[1]) + (a[2] + a[3]) + (c[0] + c[1]) + (c[2] + c[3])) * (1.f / 512.f) + RMS_EPS);
; }
;     __device__ __forceinline__ void operator()(const f32x4 (&acc)[2][2][4][2], int brow, int bcol, int wr, int wc, int fr, int fq) const {
;     ...
;                     const int row = brow + ai * 128 + wr * 64 + m * 16 + fq * 4 + j, sq = row & 4095;
;                     const float rs = rstd_from_ssq(ssq, row);
	v_add_f32_e32 v242, v225, v224
	v_add_f32_e32 v243, v226, v227
	v_add_f32_e32 v244, v210, v211
	v_add_f32_e32 v245, v208, v209
	v_add_f32_e32 v242, v242, v243
	v_add_f32_e32 v242, v242, v245
	v_add_f32_e32 v242, v244, v242
	v_fmamk_f32 v242, v242, 0x3b000000, v201
	v_cmp_gt_f32_e32 vcc, s33, v242
	v_mul_f32_e32 v243, 0x4b800000, v242
	s_nop 0
	v_cndmask_b32_e32 v242, v242, v243, vcc
	v_rsq_f32_e32 v242, v242
	s_nop 0
	v_mul_f32_e32 v243, 0x45800000, v242
	v_cndmask_b32_e32 v174, v242, v243, vcc
	s_waitcnt vmcnt(4)
	v_add_f32_e32 v242, v229, v228
	v_add_f32_e32 v243, v230, v231
	v_add_f32_e32 v244, v214, v215
	v_add_f32_e32 v245, v212, v213
	v_add_f32_e32 v242, v242, v243
	v_add_f32_e32 v242, v242, v245
	v_add_f32_e32 v242, v244, v242
	v_fmamk_f32 v242, v242, 0x3b000000, v201
	v_cmp_gt_f32_e32 vcc, s33, v242
	v_mul_f32_e32 v243, 0x4b800000, v242
	s_nop 0
	v_cndmask_b32_e32 v242, v242, v243, vcc
	v_rsq_f32_e32 v242, v242
	s_nop 0
	v_mul_f32_e32 v243, 0x45800000, v242
	v_cndmask_b32_e32 v175, v242, v243, vcc
	s_waitcnt vmcnt(2)
	v_add_f32_e32 v242, v233, v232
	v_add_f32_e32 v243, v234, v235
	v_add_f32_e32 v244, v218, v219
	v_add_f32_e32 v245, v216, v217
	v_add_f32_e32 v242, v242, v243
	v_add_f32_e32 v242, v242, v245
	v_add_f32_e32 v242, v244, v242
	v_fmamk_f32 v242, v242, 0x3b000000, v201
	v_cmp_gt_f32_e32 vcc, s33, v242
	v_mul_f32_e32 v243, 0x4b800000, v242
	s_nop 0
	v_cndmask_b32_e32 v242, v242, v243, vcc
	v_rsq_f32_e32 v242, v242
	s_nop 0
	v_mul_f32_e32 v243, 0x45800000, v242
	v_cndmask_b32_e32 v176, v242, v243, vcc
	s_waitcnt vmcnt(0)
	v_add_f32_e32 v242, v237, v236
	v_add_f32_e32 v243, v238, v239
	v_add_f32_e32 v244, v222, v223
	v_add_f32_e32 v245, v220, v221
	v_add_f32_e32 v242, v242, v243
	v_add_f32_e32 v242, v242, v245
	v_add_f32_e32 v242, v244, v242
	v_fmamk_f32 v242, v242, 0x3b000000, v201
	v_cmp_gt_f32_e32 vcc, s33, v242
	v_mul_f32_e32 v243, 0x4b800000, v242
	s_nop 0
	v_cndmask_b32_e32 v242, v242, v243, vcc
	v_rsq_f32_e32 v242, v242
	s_nop 0
	v_mul_f32_e32 v243, 0x45800000, v242
	v_cndmask_b32_e32 v177, v242, v243, vcc
	v_add_u32_e32 v240, 0xa1, v134
	v_ashrrev_i32_e32 v241, 31, v240
	v_lshlrev_b64 v[240:241], 5, v[240:241]
	v_lshl_add_u64 v[240:241], s[46:47], 0, v[240:241]
	global_load_dwordx4 v[208:211], v[240:241], off offset:16
	global_load_dwordx4 v[224:227], v[240:241], off
	v_add_u32_e32 v240, 0xa2, v134
	v_ashrrev_i32_e32 v241, 31, v240
	v_lshlrev_b64 v[240:241], 5, v[240:241]
	v_lshl_add_u64 v[240:241], s[46:47], 0, v[240:241]
	global_load_dwordx4 v[212:215], v[240:241], off offset:16
	global_load_dwordx4 v[228:231], v[240:241], off
	v_add_u32_e32 v240, 0xa3, v134
	v_ashrrev_i32_e32 v241, 31, v240
	v_lshlrev_b64 v[240:241], 5, v[240:241]
	v_lshl_add_u64 v[240:241], s[46:47], 0, v[240:241]
	global_load_dwordx4 v[216:219], v[240:241], off offset:16
	global_load_dwordx4 v[232:235], v[240:241], off
	v_add_u32_e32 v240, 0xb0, v134
	v_ashrrev_i32_e32 v241, 31, v240
	v_lshlrev_b64 v[240:241], 5, v[240:241]
	v_lshl_add_u64 v[240:241], s[46:47], 0, v[240:241]
	global_load_dwordx4 v[220:223], v[240:241], off offset:16
	global_load_dwordx4 v[236:239], v[240:241], off
	s_waitcnt vmcnt(6)
	v_add_f32_e32 v242, v225, v224
	v_add_f32_e32 v243, v226, v227
	v_add_f32_e32 v244, v210, v211
	v_add_f32_e32 v245, v208, v209
	v_add_f32_e32 v242, v242, v243
	v_add_f32_e32 v242, v242, v245
	v_add_f32_e32 v242, v244, v242
	v_fmamk_f32 v242, v242, 0x3b000000, v201
	v_cmp_gt_f32_e32 vcc, s33, v242
	v_mul_f32_e32 v243, 0x4b800000, v242
	s_nop 0
	v_cndmask_b32_e32 v242, v242, v243, vcc
	v_rsq_f32_e32 v242, v242
	s_nop 0
	v_mul_f32_e32 v243, 0x45800000, v242
	v_cndmask_b32_e32 v178, v242, v243, vcc
	s_waitcnt vmcnt(4)
	v_add_f32_e32 v242, v229, v228
	v_add_f32_e32 v243, v230, v231
	v_add_f32_e32 v244, v214, v215
	v_add_f32_e32 v245, v212, v213
	v_add_f32_e32 v242, v242, v243
	v_add_f32_e32 v242, v242, v245
	v_add_f32_e32 v242, v244, v242
	v_fmamk_f32 v242, v242, 0x3b000000, v201
	v_cmp_gt_f32_e32 vcc, s33, v242
	v_mul_f32_e32 v243, 0x4b800000, v242
	s_nop 0
	v_cndmask_b32_e32 v242, v242, v243, vcc
	v_rsq_f32_e32 v242, v242
	s_nop 0
	v_mul_f32_e32 v243, 0x45800000, v242
	v_cndmask_b32_e32 v179, v242, v243, vcc
	s_waitcnt vmcnt(2)
	v_add_f32_e32 v242, v233, v232
	v_add_f32_e32 v243, v234, v235
	v_add_f32_e32 v244, v218, v219
	v_add_f32_e32 v245, v216, v217
	v_add_f32_e32 v242, v242, v243
	v_add_f32_e32 v242, v242, v245
	v_add_f32_e32 v242, v244, v242
	v_fmamk_f32 v242, v242, 0x3b000000, v201
	v_cmp_gt_f32_e32 vcc, s33, v242
	v_mul_f32_e32 v243, 0x4b800000, v242
	s_nop 0
	v_cndmask_b32_e32 v242, v242, v243, vcc
	v_rsq_f32_e32 v242, v242
	s_nop 0
	v_mul_f32_e32 v243, 0x45800000, v242
	v_cndmask_b32_e32 v180, v242, v243, vcc
	s_waitcnt vmcnt(0)
; #define GAS __attribute__((address_space(1)))
; __device__ __forceinline__ unsigned cvtpk(float lo, float hi) { return __builtin_bit_cast(unsigned, __builtin_convertvector(f32x2_cv{lo, hi}, bf16x2_cv)); }
; __device__ __forceinline__ bf16_t f2bf(float f) { return (bf16_t)(cvtpk(f, 0.f) & 0xffffu); }
; __device__ __forceinline__ float rstd_from_ssq(const float* __restrict__ ssq, int row) {
;     const f32x4 a = *(const GAS f32x4*)(ssq + (size_t)row * 8), c = *(const GAS f32x4*)(ssq + (size_t)row * 8 + 4);
;     return rsqrtf(((a[0] + a[1]) + (a[2] + a[3]) + (c[0] + c[1]) + (c[2] + c[3])) * (1.f / 512.f) + RMS_EPS);
; }
;     __device__ __forceinline__ void operator()(const f32x4 (&acc)[2][2][4][2], int brow, int bcol, int wr, int wc, int fr, int fq) const {
;     ...
;                     const int row = brow + ai * 128 + wr * 64 + m * 16 + fq * 4 + j, sq = row & 4095;
;                     const float rs = rstd_from_ssq(ssq, row);
;                     if (bcol < 1024) {
; #pragma unroll
;                         for (int bj = 0; bj < 2; ++bj)
;                             *(GAS unsigned*)(qm + ((size_t)(b * 8 + (bcol >> 7) + bj) * S + sq) * 192 + wc * 32 + 2 * fr) = cvtpk(acc[ai][bj][m][0][j] * rs, acc[ai][bj][m][1][j] * rs);
;                     } else {
;                         const int i = (wc & 1) * 16 + fr;
;                         const float2 cs = r64[sq * 32 + i];
; #pragma unroll
;                         for (int bj = 0; bj < 2; ++bj) {
;                             const int head = ((bcol - 1024) >> 8) * 4 + bj * 2 + (wc >> 1);
;                             const float x1 = acc[ai][bj][m][0][j] * rs, x2 = acc[ai][bj][m][1][j] * rs;
;                             GAS bf16_t* p = (GAS bf16_t*)(qm + ((size_t)(b * 8 + head) * S + sq) * 192 + 128);
;                             p[i] = f2bf(x1 * cs.x - x2 * cs.y); p[32 + i] = f2bf(x2 * cs.x + x1 * cs.y);
;                         }
	v_add_f32_e32 v242, v237, v236
	v_add_f32_e32 v243, v238, v239
	v_add_f32_e32 v244, v222, v223
	v_add_f32_e32 v245, v220, v221
	v_add_f32_e32 v242, v242, v243
	v_add_f32_e32 v242, v242, v245
	v_add_f32_e32 v242, v244, v242
	v_fmamk_f32 v242, v242, 0x3b000000, v201
	v_cmp_gt_f32_e32 vcc, s33, v242
	v_mul_f32_e32 v243, 0x4b800000, v242
	s_nop 0
	v_cndmask_b32_e32 v242, v242, v243, vcc
	v_rsq_f32_e32 v242, v242
	s_nop 0
	v_mul_f32_e32 v243, 0x45800000, v242
	v_cndmask_b32_e32 v181, v242, v243, vcc
	v_add_u32_e32 v240, 0xb1, v134
	v_ashrrev_i32_e32 v241, 31, v240
	v_lshlrev_b64 v[240:241], 5, v[240:241]
	v_lshl_add_u64 v[240:241], s[46:47], 0, v[240:241]
	global_load_dwordx4 v[208:211], v[240:241], off offset:16
	global_load_dwordx4 v[224:227], v[240:241], off
	v_add_u32_e32 v240, 0xb2, v134
	v_ashrrev_i32_e32 v241, 31, v240
	v_lshlrev_b64 v[240:241], 5, v[240:241]
	v_lshl_add_u64 v[240:241], s[46:47], 0, v[240:241]
	global_load_dwordx4 v[212:215], v[240:241], off offset:16
	global_load_dwordx4 v[228:231], v[240:241], off
	v_add_u32_e32 v240, 0xb3, v134
	v_ashrrev_i32_e32 v241, 31, v240
	v_lshlrev_b64 v[240:241], 5, v[240:241]
	v_lshl_add_u64 v[240:241], s[46:47], 0, v[240:241]
	global_load_dwordx4 v[216:219], v[240:241], off offset:16
	global_load_dwordx4 v[232:235], v[240:241], off
	s_waitcnt vmcnt(4)
	v_add_f32_e32 v242, v225, v224
	v_add_f32_e32 v243, v226, v227
	v_add_f32_e32 v244, v210, v211
	v_add_f32_e32 v245, v208, v209
	v_add_f32_e32 v242, v242, v243
	v_add_f32_e32 v242, v242, v245
	v_add_f32_e32 v242, v244, v242
	v_fmamk_f32 v242, v242, 0x3b000000, v201
	v_cmp_gt_f32_e32 vcc, s33, v242
	v_mul_f32_e32 v243, 0x4b800000, v242
	s_nop 0
	v_cndmask_b32_e32 v242, v242, v243, vcc
	v_rsq_f32_e32 v242, v242
	s_nop 0
	v_mul_f32_e32 v243, 0x45800000, v242
	v_cndmask_b32_e32 v182, v242, v243, vcc
	s_waitcnt vmcnt(2)
	v_add_f32_e32 v242, v229, v228
	v_add_f32_e32 v243, v230, v231
	v_add_f32_e32 v244, v214, v215
	v_add_f32_e32 v245, v212, v213
	v_add_f32_e32 v242, v242, v243
	v_add_f32_e32 v242, v242, v245
	v_add_f32_e32 v242, v244, v242
	v_fmamk_f32 v242, v242, 0x3b000000, v201
	v_cmp_gt_f32_e32 vcc, s33, v242
	v_mul_f32_e32 v243, 0x4b800000, v242
	s_nop 0
	v_cndmask_b32_e32 v242, v242, v243, vcc
	v_rsq_f32_e32 v242, v242
	s_nop 0
	v_mul_f32_e32 v243, 0x45800000, v242
	v_cndmask_b32_e32 v183, v242, v243, vcc
	s_waitcnt vmcnt(0)
	v_add_f32_e32 v242, v233, v232
	v_add_f32_e32 v243, v234, v235
	v_add_f32_e32 v244, v218, v219
	v_add_f32_e32 v245, v216, v217
	v_add_f32_e32 v242, v242, v243
	v_add_f32_e32 v242, v242, v245
	v_add_f32_e32 v242, v244, v242
	v_fmamk_f32 v242, v242, 0x3b000000, v201
	v_cmp_gt_f32_e32 vcc, s33, v242
	v_mul_f32_e32 v243, 0x4b800000, v242
	s_nop 0
	v_cndmask_b32_e32 v242, v242, v243, vcc
	v_rsq_f32_e32 v242, v242
	s_nop 0
	v_mul_f32_e32 v243, 0x45800000, v242
	v_cndmask_b32_e32 v184, v242, v243, vcc
	v_lshlrev_b64 v[136:137], 5, v[134:135]
	v_lshl_add_u64 v[144:145], s[46:47], 0, v[136:137]
	global_load_dwordx4 v[136:139], v[144:145], off offset:16
	s_nop 0
	global_load_dwordx4 v[144:147], v[144:145], off
	s_cmp_gt_i32 s16, 3
	s_cselect_b64 s[54:55], -1, 0
	s_add_i32 s12, s40, 0xfffffc00
	s_lshr_b32 s13, s12, 6
	s_ashr_i32 s12, s17, 1
	s_and_b32 s12, s12, -8
	v_lshrrev_b32_e32 v2, 6, v132
	v_lshrrev_b32_e32 v132, 1, v141
	s_add_i32 s13, s13, s12
	v_or_b32_e32 v132, s13, v132
	s_movk_i32 s13, 0xfcc
	v_bitop3_b32 v143, v133, s13, v1 bitop3:0xc8
	v_lshlrev_b32_e32 v2, 4, v2
	v_and_or_b32 v2, v2, 16, v140
	s_mov_b64 s[40:41], -1
	s_waitcnt vmcnt(0)
	v_mov_b32_e32 v148, v145
	v_mov_b32_e32 v149, v146
	v_mov_b32_e32 v145, v147
	v_pk_add_f32 v[144:145], v[148:149], v[144:145]
	v_mov_b32_e32 v146, v138
	v_mov_b32_e32 v147, v136
	v_mov_b32_e32 v136, v139
	v_pk_add_f32 v[136:137], v[146:147], v[136:137]
	v_add_f32_e32 v1, v144, v145
	v_add_f32_e32 v1, v1, v137
	v_add_f32_e32 v1, v136, v1
	v_fmamk_f32 v1, v1, 0x3b000000, v201
	v_cmp_gt_f32_e32 vcc, s33, v1
	v_mul_f32_e32 v133, 0x4b800000, v1
	v_or_b32_e32 v138, 2, v132
	v_cndmask_b32_e32 v1, v1, v133, vcc
	v_rsq_f32_e32 v1, v1
	v_lshlrev_b32_e32 v136, 1, v2
	v_ashrrev_i32_e32 v139, 31, v138
	v_mul_f32_e32 v133, 0x45800000, v1
	v_cndmask_b32_e32 v142, v1, v133, vcc
	s_and_b64 vcc, exec, s[54:55]
	v_ashrrev_i32_e32 v133, 31, v132
	v_lshlrev_b32_e32 v1, 3, v2
	s_cbranch_vccz .LBB0_753
	v_lshl_or_b32 v2, v143, 8, v1
	v_lshl_add_u64 v[144:145], s[50:51], 0, v[2:3]
	flat_load_dwordx2 v[144:145], v[144:145]
	v_lshlrev_b64 v[146:147], 12, v[132:133]
	v_mul_f32_e32 v135, v116, v142
	v_or_b32_e32 v137, v146, v143
	v_mov_b64_e32 v[148:149], s[48:49]
	v_mul_f32_e32 v2, v120, v142
	v_mad_u64_u32 v[150:151], s[28:29], v137, s69, v[148:149]
	v_mad_i32_i24 v151, v147, s69, v151
	s_mov_b64 s[40:41], 0
	s_waitcnt vmcnt(0) lgkmcnt(0)
	v_mul_f32_e32 v137, v135, v145
	v_fma_f32 v137, v2, v144, -v137
	v_mul_f32_e32 v2, v2, v145
	v_cvt_pk_bf16_f32 v152, v137, s0
	v_mov_b32_e32 v137, v3
	v_fmac_f32_e32 v2, v135, v144
	v_lshl_add_u64 v[146:147], v[150:151], 0, v[136:137]
	v_cvt_pk_bf16_f32 v2, v2, s0
	global_store_short v[146:147], v152, off offset:256
	global_store_short v[146:147], v2, off offset:320
	v_lshlrev_b64 v[146:147], 12, v[138:139]
	v_mul_f32_e32 v135, v128, v142
	v_or_b32_e32 v146, v146, v143
	v_mul_f32_e32 v2, v124, v142
	v_mad_u64_u32 v[148:149], s[28:29], v146, s69, v[148:149]
	v_mul_f32_e32 v146, v135, v145
	v_fma_f32 v146, v2, v144, -v146
	v_mul_f32_e32 v2, v2, v145
	v_mad_i32_i24 v149, v147, s69, v149
	v_fmac_f32_e32 v2, v135, v144
	v_cvt_pk_bf16_f32 v150, v146, s0
	v_lshl_add_u64 v[146:147], v[148:149], 0, v[136:137]
	v_cvt_pk_bf16_f32 v2, v2, s0
	global_store_short v[146:147], v150, off offset:256
	global_store_short v[146:147], v2, off offset:320

; #define GAS __attribute__((address_space(1)))
; __device__ __forceinline__ unsigned cvtpk(float lo, float hi) { return __builtin_bit_cast(unsigned, __builtin_convertvector(f32x2_cv{lo, hi}, bf16x2_cv)); }
; __device__ __forceinline__ float rstd_from_ssq(const float* __restrict__ ssq, int row) {
;     const f32x4 a = *(const GAS f32x4*)(ssq + (size_t)row * 8), c = *(const GAS f32x4*)(ssq + (size_t)row * 8 + 4);
;     return rsqrtf(((a[0] + a[1]) + (a[2] + a[3]) + (c[0] + c[1]) + (c[2] + c[3])) * (1.f / 512.f) + RMS_EPS);
; }
;     __device__ __forceinline__ void operator()(const f32x4 (&acc)[2][2][4][2], int brow, int bcol, int wr, int wc, int fr, int fq) const {
;     ...
;                 const int row0 = brow + ai * 128 + wr * 64 + m * 16 + fq * 4, s0 = row0 & 4095;
;                 float rs[4];
; #pragma unroll
;                 for (int j = 0; j < 4; ++j) rs[j] = rstd_from_ssq(ssq, row0 + j);
; #pragma unroll
;                 for (int j = 0; j < 4; ++j)
;                     *(GAS unsigned*)(km + ((size_t)(b * 8 + head) * S + s0 + j) * 192 + wc * 32 + 2 * fr) = cvtpk(acc[ai][0][m][0][j] * rs[j], acc[ai][0][m][1][j] * rs[j]);
.LBB0_880:
	s_or_b64 exec, exec, s[12:13]
	v_lshlrev_b32_e32 v144, 2, v132
	v_add_u32_e32 v145, s52, v143
	v_or_b32_e32 v136, v145, v144
	v_and_b32_e32 v251, 0xffffff00, v136
	v_lshlrev_b32_e32 v251, 5, v251
	v_lshl_add_u32 v250, v0, 4, v251
	v_mov_b32_e32 v251, 0
	v_lshl_add_u64 v[250:251], s[48:49], 0, v[250:251]
	global_load_dwordx4 v[252:255], v[250:251], off
	v_lshlrev_b32_e32 v2, 6, v142
	v_lshl_add_u64 v[132:133], s[50:51], 0, v[2:3]
	v_lshlrev_b32_e32 v134, 2, v139
	v_mov_b32_e32 v135, v3
	v_ashrrev_i32_e32 v137, 31, v136
	v_lshl_add_u64 v[134:135], v[132:133], 0, v[134:135]
	v_lshlrev_b64 v[132:133], 5, v[136:137]
	v_lshl_add_u64 v[132:133], s[48:49], 0, v[132:133]
	global_load_dwordx4 v[146:149], v[132:133], off offset:48
	global_load_dwordx4 v[150:153], v[132:133], off offset:32
	global_load_dwordx4 v[154:157], v[132:133], off offset:16
	global_load_dwordx4 v[158:161], v[132:133], off
	s_ashr_i32 s12, s16, 1
	s_and_b32 s12, s12, -8
	s_add_i32 s56, s12, s17
	s_mov_b32 s12, 0x358637bd
	s_mov_b32 s58, 0x3b000000
	s_ashr_i32 s57, s56, 31
	s_lshl_b64 s[40:41], s[56:57], 12
	s_mov_b32 s54, 0x45800000
	v_and_b32_e32 v1, 0xffffff00, v1
	v_or3_b32 v1, v2, v1, v141
	v_and_or_b32 v2, v141, 16, v139
	v_lshlrev_b32_e32 v2, 4, v2
	s_waitcnt vmcnt(0)
	v_mov_b32_e32 v132, v159
	v_mov_b32_e32 v133, v160
	v_mov_b32_e32 v159, v161
	v_pk_add_f32 v[132:133], v[132:133], v[158:159]
	v_mov_b32_e32 v158, v156
	v_mov_b32_e32 v159, v154
	v_mov_b32_e32 v154, v157
	v_mov_b32_e32 v156, v151
	v_mov_b32_e32 v157, v152
	v_mov_b32_e32 v151, v153
	v_pk_add_f32 v[150:151], v[156:157], v[150:151]
	v_mov_b32_e32 v152, v148
	v_mov_b32_e32 v153, v146
	v_mov_b32_e32 v146, v149
	v_pk_add_f32 v[154:155], v[158:159], v[154:155]
	v_pk_add_f32 v[146:147], v[152:153], v[146:147]
	v_mov_b32_e32 v148, v150
	v_mov_b32_e32 v149, v132
	v_mov_b32_e32 v132, v151
	v_pk_add_f32 v[132:133], v[148:149], v[132:133]
	v_mov_b32_e32 v148, v147
	v_mov_b32_e32 v149, v155
	v_pk_add_f32 v[132:133], v[132:133], v[148:149]
	v_mov_b32_e32 v147, v154
	v_pk_add_f32 v[146:147], v[146:147], v[132:133]
	v_mov_b64_e32 v[132:133], s[12:13]
	v_pk_fma_f32 v[146:147], v[146:147], s[58:59], v[132:133] op_sel_hi:[1,0,0]
	s_movk_i32 s12, 0xfcc
	v_mul_f32_e32 v137, 0x4b800000, v147
	v_cmp_gt_f32_e64 s[42:43], s33, v147
	v_cmp_gt_f32_e32 vcc, s33, v146
	s_nop 0
	v_cndmask_b32_e64 v137, v147, v137, s[42:43]
	v_rsq_f32_e32 v137, v137
	s_nop 0
	v_mul_f32_e32 v138, 0x45800000, v137
	v_cndmask_b32_e64 v140, v137, v138, s[42:43]
	v_mul_f32_e32 v137, 0x4b800000, v146
	v_cndmask_b32_e32 v137, v146, v137, vcc
	v_or_b32_e32 v146, 2, v136
	v_ashrrev_i32_e32 v147, 31, v146
	v_lshlrev_b64 v[146:147], 5, v[146:147]
	v_lshl_add_u64 v[158:159], s[48:49], 0, v[146:147]
	global_load_dwordx4 v[146:149], v[158:159], off offset:48
	global_load_dwordx4 v[150:153], v[158:159], off offset:32
	global_load_dwordx4 v[154:157], v[158:159], off offset:16
	s_nop 0
	global_load_dwordx4 v[158:161], v[158:159], off
	v_rsq_f32_e32 v137, v137
	s_waitcnt vmcnt(0)
	v_mov_b32_e32 v162, v159
	v_mov_b32_e32 v163, v160
	v_mov_b32_e32 v159, v161
	v_mov_b32_e32 v160, v156
	v_mov_b32_e32 v161, v154
	v_mov_b32_e32 v154, v157
	v_mov_b32_e32 v156, v151
	v_mov_b32_e32 v157, v152
	v_mov_b32_e32 v151, v153
	v_pk_add_f32 v[158:159], v[162:163], v[158:159]
	v_pk_add_f32 v[150:151], v[156:157], v[150:151]
	v_mov_b32_e32 v152, v148
	v_mov_b32_e32 v153, v146
	v_mov_b32_e32 v146, v149
	v_pk_add_f32 v[154:155], v[160:161], v[154:155]
	v_pk_add_f32 v[146:147], v[152:153], v[146:147]
	v_mov_b32_e32 v148, v150
	v_mov_b32_e32 v149, v158
	v_mov_b32_e32 v158, v151
	v_pk_add_f32 v[148:149], v[148:149], v[158:159]
	v_mov_b32_e32 v150, v147
	v_mov_b32_e32 v151, v155
	v_pk_add_f32 v[148:149], v[148:149], v[150:151]
	v_mov_b32_e32 v147, v154
	v_pk_add_f32 v[146:147], v[146:147], v[148:149]
	v_mul_f32_e32 v138, 0x45800000, v137
	v_pk_fma_f32 v[146:147], v[146:147], s[58:59], v[132:133] op_sel_hi:[1,0,0]
	v_cndmask_b32_e32 v138, v137, v138, vcc
	v_mul_f32_e32 v137, 0x4b800000, v147
	v_cmp_gt_f32_e64 s[42:43], s33, v147
	v_cmp_gt_f32_e32 vcc, s33, v146
	v_mov_b32_e32 v150, v128
	v_cndmask_b32_e64 v137, v147, v137, s[42:43]
	v_rsq_f32_e32 v137, v137
	v_mov_b32_e32 v151, v124
	v_pk_mul_f32 v[150:151], v[150:151], v[140:141] op_sel_hi:[1,0]
	v_mul_f32_e32 v147, 0x45800000, v137
	v_cndmask_b32_e64 v148, v137, v147, s[42:43]
	v_mul_f32_e32 v137, 0x4b800000, v146
	v_cndmask_b32_e32 v137, v146, v137, vcc
	v_rsq_f32_e32 v137, v137
	v_cvt_pk_bf16_f32 v124, v150, v151
	v_mul_f32_e32 v146, 0x45800000, v137
	v_cndmask_b32_e32 v146, v137, v146, vcc
	v_bitop3_b32 v137, v145, s12, v144 bitop3:0xc8
	v_or_b32_e32 v137, s40, v137
	v_mad_u64_u32 v[150:151], s[12:13], v137, s69, v[134:135]
	v_mad_i32_i24 v151, s41, v207, v151
	global_store_dword v[150:151], v124, off
	v_mov_b32_e32 v124, v129
	v_pk_mul_f32 v[124:125], v[124:125], v[138:139] op_sel_hi:[1,0]
	s_movk_i32 s12, 0xfdc
	v_cvt_pk_bf16_f32 v124, v124, v125
	global_store_dword v[150:151], v124, off offset:384
	v_mov_b32_e32 v124, v130
	v_mov_b32_e32 v125, v126
	v_pk_mul_f32 v[124:125], v[124:125], v[148:149] op_sel_hi:[1,0]
	v_mov_b32_e32 v126, v131
	v_cvt_pk_bf16_f32 v124, v124, v125
	global_store_dword v[150:151], v124, off offset:768
	v_pk_mul_f32 v[124:125], v[126:127], v[146:147] op_sel_hi:[1,0]
	s_nop 0
	v_cvt_pk_bf16_f32 v124, v124, v125
	global_store_dword v[150:151], v124, off offset:1152
	v_or_b32_e32 v124, 16, v136
	v_ashrrev_i32_e32 v125, 31, v124
	v_lshlrev_b64 v[124:125], 5, v[124:125]
	v_lshl_add_u64 v[150:151], s[48:49], 0, v[124:125]
	global_load_dwordx4 v[124:127], v[150:151], off offset:48
	global_load_dwordx4 v[128:131], v[150:151], off offset:32
	global_load_dwordx4 v[146:149], v[150:151], off offset:16
	s_nop 0
	global_load_dwordx4 v[150:153], v[150:151], off
	s_waitcnt vmcnt(0)
; #define GAS __attribute__((address_space(1)))
; __device__ __forceinline__ unsigned cvtpk(float lo, float hi) { return __builtin_bit_cast(unsigned, __builtin_convertvector(f32x2_cv{lo, hi}, bf16x2_cv)); }
; __device__ __forceinline__ float rstd_from_ssq(const float* __restrict__ ssq, int row) {
;     const f32x4 a = *(const GAS f32x4*)(ssq + (size_t)row * 8), c = *(const GAS f32x4*)(ssq + (size_t)row * 8 + 4);
;     return rsqrtf(((a[0] + a[1]) + (a[2] + a[3]) + (c[0] + c[1]) + (c[2] + c[3])) * (1.f / 512.f) + RMS_EPS);
; }
;     __device__ __forceinline__ void operator()(const f32x4 (&acc)[2][2][4][2], int brow, int bcol, int wr, int wc, int fr, int fq) const {
;     ...
;                 const int row0 = brow + ai * 128 + wr * 64 + m * 16 + fq * 4, s0 = row0 & 4095;
;                 float rs[4];
; #pragma unroll
;                 for (int j = 0; j < 4; ++j) rs[j] = rstd_from_ssq(ssq, row0 + j);
; #pragma unroll
;                 for (int j = 0; j < 4; ++j)
;                     *(GAS unsigned*)(km + ((size_t)(b * 8 + head) * S + s0 + j) * 192 + wc * 32 + 2 * fr) = cvtpk(acc[ai][0][m][0][j] * rs[j], acc[ai][0][m][1][j] * rs[j]);
	v_mov_b32_e32 v154, v151
	v_mov_b32_e32 v155, v152
	v_mov_b32_e32 v151, v153
	v_mov_b32_e32 v152, v148
	v_mov_b32_e32 v153, v146
	v_mov_b32_e32 v146, v149
	v_mov_b32_e32 v148, v129
	v_mov_b32_e32 v149, v130
	v_mov_b32_e32 v129, v131
	v_pk_add_f32 v[150:151], v[154:155], v[150:151]
	v_pk_add_f32 v[128:129], v[148:149], v[128:129]
	v_mov_b32_e32 v130, v126
	v_mov_b32_e32 v131, v124
	v_mov_b32_e32 v124, v127
	v_pk_add_f32 v[146:147], v[152:153], v[146:147]
	v_pk_add_f32 v[124:125], v[130:131], v[124:125]
	v_mov_b32_e32 v126, v128
	v_mov_b32_e32 v127, v150
	v_mov_b32_e32 v150, v129
	v_pk_add_f32 v[126:127], v[126:127], v[150:151]
	v_mov_b32_e32 v128, v125
	v_mov_b32_e32 v129, v147
	v_pk_add_f32 v[126:127], v[126:127], v[128:129]
	v_or_b32_e32 v128, 18, v136
	v_ashrrev_i32_e32 v129, 31, v128
	v_lshlrev_b64 v[128:129], 5, v[128:129]
	v_lshl_add_u64 v[154:155], s[48:49], 0, v[128:129]
	v_mov_b32_e32 v125, v146
	global_load_dwordx4 v[128:131], v[154:155], off offset:48
	global_load_dwordx4 v[146:149], v[154:155], off offset:32
	global_load_dwordx4 v[150:153], v[154:155], off offset:16
	s_nop 0
	global_load_dwordx4 v[154:157], v[154:155], off
	v_pk_add_f32 v[124:125], v[124:125], v[126:127]
	s_waitcnt vmcnt(0)
	v_mov_b32_e32 v158, v155
	v_pk_fma_f32 v[124:125], v[124:125], s[58:59], v[132:133] op_sel_hi:[1,0,0]
	v_mov_b32_e32 v159, v156
	v_mul_f32_e32 v126, 0x4b800000, v125
	v_cmp_gt_f32_e64 s[42:43], s33, v125
	v_cmp_gt_f32_e32 vcc, s33, v124
	v_mov_b32_e32 v155, v157
	v_cndmask_b32_e64 v125, v125, v126, s[42:43]
	v_rsq_f32_e32 v125, v125
	v_mov_b32_e32 v156, v152
	v_mov_b32_e32 v157, v150
	v_mov_b32_e32 v150, v153
	v_mul_f32_e32 v126, 0x45800000, v125
	v_cndmask_b32_e64 v126, v125, v126, s[42:43]
	v_mul_f32_e32 v125, 0x4b800000, v124
	v_mov_b32_e32 v152, v147
	v_mov_b32_e32 v153, v148
	v_mov_b32_e32 v147, v149
	v_cndmask_b32_e32 v124, v124, v125, vcc
	v_pk_add_f32 v[154:155], v[158:159], v[154:155]
	v_pk_add_f32 v[146:147], v[152:153], v[146:147]
	v_mov_b32_e32 v148, v130
	v_mov_b32_e32 v149, v128
	v_mov_b32_e32 v128, v131
	v_rsq_f32_e32 v124, v124
	v_pk_add_f32 v[150:151], v[156:157], v[150:151]
	v_pk_add_f32 v[128:129], v[148:149], v[128:129]
	v_mov_b32_e32 v130, v146
	v_mov_b32_e32 v131, v154
	v_mov_b32_e32 v154, v147
	v_pk_add_f32 v[130:131], v[130:131], v[154:155]
	v_mov_b32_e32 v146, v129
	v_mov_b32_e32 v147, v151
	v_pk_add_f32 v[130:131], v[130:131], v[146:147]
	v_mov_b32_e32 v129, v150
	v_pk_add_f32 v[128:129], v[128:129], v[130:131]
	v_mul_f32_e32 v125, 0x45800000, v124
	v_pk_fma_f32 v[128:129], v[128:129], s[58:59], v[132:133] op_sel_hi:[1,0,0]
	v_cndmask_b32_e32 v124, v124, v125, vcc
	v_mul_f32_e32 v125, 0x4b800000, v129
	v_cmp_gt_f32_e64 s[42:43], s33, v129
	v_cmp_gt_f32_e32 vcc, s33, v128
	v_mov_b32_e32 v146, v120
	v_cndmask_b32_e64 v125, v129, v125, s[42:43]
	v_rsq_f32_e32 v125, v125
	v_mov_b32_e32 v147, v116
	v_mul_f32_e32 v127, 0x45800000, v125
	v_cndmask_b32_e64 v130, v125, v127, s[42:43]
	v_mul_f32_e32 v125, 0x4b800000, v128
	v_cndmask_b32_e32 v125, v128, v125, vcc
	v_rsq_f32_e32 v125, v125
	s_nop 0
	v_mul_f32_e32 v127, 0x45800000, v125
	v_cndmask_b32_e32 v128, v125, v127, vcc
	v_bitop3_b32 v125, v136, s12, 16 bitop3:0xc8
	v_or_b32_e32 v125, s40, v125
	v_pk_mul_f32 v[126:127], v[146:147], v[126:127] op_sel_hi:[1,0]
	s_nop 0
	v_cvt_pk_bf16_f32 v116, v126, v127
	v_mad_u64_u32 v[126:127], s[12:13], v125, s69, v[134:135]
	v_mad_i32_i24 v127, s41, v207, v127
	global_store_dword v[126:127], v116, off
	v_mov_b32_e32 v116, v121
	v_pk_mul_f32 v[116:117], v[116:117], v[124:125] op_sel_hi:[1,0]
	s_movk_i32 s12, 0xfec
	v_cvt_pk_bf16_f32 v116, v116, v117
	global_store_dword v[126:127], v116, off offset:384
	v_mov_b32_e32 v116, v122
	v_mov_b32_e32 v117, v118
	v_pk_mul_f32 v[116:117], v[116:117], v[130:131] op_sel_hi:[1,0]
	v_mov_b32_e32 v118, v123
	v_cvt_pk_bf16_f32 v116, v116, v117
	global_store_dword v[126:127], v116, off offset:768
	v_pk_mul_f32 v[116:117], v[118:119], v[128:129] op_sel_hi:[1,0]
	s_nop 0
	v_cvt_pk_bf16_f32 v116, v116, v117
	global_store_dword v[126:127], v116, off offset:1152
	v_or_b32_e32 v116, 32, v136
	v_ashrrev_i32_e32 v117, 31, v116
	v_lshlrev_b64 v[116:117], 5, v[116:117]
	v_lshl_add_u64 v[128:129], s[48:49], 0, v[116:117]
	global_load_dwordx4 v[116:119], v[128:129], off offset:48
	global_load_dwordx4 v[120:123], v[128:129], off offset:32
	global_load_dwordx4 v[124:127], v[128:129], off offset:16
	s_nop 0
	global_load_dwordx4 v[128:131], v[128:129], off
	s_waitcnt vmcnt(0)
	v_mov_b32_e32 v146, v129
	v_mov_b32_e32 v147, v130
	v_mov_b32_e32 v129, v131
	v_mov_b32_e32 v130, v126
	v_mov_b32_e32 v131, v124
	v_mov_b32_e32 v124, v127
	v_mov_b32_e32 v126, v121
	v_mov_b32_e32 v127, v122
	v_mov_b32_e32 v121, v123
	v_pk_add_f32 v[128:129], v[146:147], v[128:129]
	v_pk_add_f32 v[120:121], v[126:127], v[120:121]
	v_mov_b32_e32 v122, v118
	v_mov_b32_e32 v123, v116
	v_mov_b32_e32 v116, v119
	v_pk_add_f32 v[124:125], v[130:131], v[124:125]
	v_pk_add_f32 v[116:117], v[122:123], v[116:117]
	v_mov_b32_e32 v118, v120
	v_mov_b32_e32 v119, v128
	v_mov_b32_e32 v128, v121
	v_pk_add_f32 v[118:119], v[118:119], v[128:129]
	v_mov_b32_e32 v120, v117
	v_mov_b32_e32 v121, v125
	v_pk_add_f32 v[118:119], v[118:119], v[120:121]
	v_or_b32_e32 v120, 34, v136
	v_ashrrev_i32_e32 v121, 31, v120
	v_lshlrev_b64 v[120:121], 5, v[120:121]
	v_lshl_add_u64 v[146:147], s[48:49], 0, v[120:121]
	v_mov_b32_e32 v117, v124
	global_load_dwordx4 v[120:123], v[146:147], off offset:48
	global_load_dwordx4 v[124:127], v[146:147], off offset:32
	global_load_dwordx4 v[128:131], v[146:147], off offset:16
	s_nop 0
	global_load_dwordx4 v[146:149], v[146:147], off
	v_pk_add_f32 v[116:117], v[116:117], v[118:119]
	s_waitcnt vmcnt(0)
; #define GAS __attribute__((address_space(1)))
; __device__ __forceinline__ unsigned cvtpk(float lo, float hi) { return __builtin_bit_cast(unsigned, __builtin_convertvector(f32x2_cv{lo, hi}, bf16x2_cv)); }
; __device__ __forceinline__ float rstd_from_ssq(const float* __restrict__ ssq, int row) {
;     const f32x4 a = *(const GAS f32x4*)(ssq + (size_t)row * 8), c = *(const GAS f32x4*)(ssq + (size_t)row * 8 + 4);
;     return rsqrtf(((a[0] + a[1]) + (a[2] + a[3]) + (c[0] + c[1]) + (c[2] + c[3])) * (1.f / 512.f) + RMS_EPS);
; }
;     __device__ __forceinline__ void operator()(const f32x4 (&acc)[2][2][4][2], int brow, int bcol, int wr, int wc, int fr, int fq) const {
;     ...
;                 const int row0 = brow + ai * 128 + wr * 64 + m * 16 + fq * 4, s0 = row0 & 4095;
;                 float rs[4];
; #pragma unroll
;                 for (int j = 0; j < 4; ++j) rs[j] = rstd_from_ssq(ssq, row0 + j);
; #pragma unroll
;                 for (int j = 0; j < 4; ++j)
;                     *(GAS unsigned*)(km + ((size_t)(b * 8 + head) * S + s0 + j) * 192 + wc * 32 + 2 * fr) = cvtpk(acc[ai][0][m][0][j] * rs[j], acc[ai][0][m][1][j] * rs[j]);
	v_mov_b32_e32 v150, v147
	v_pk_fma_f32 v[116:117], v[116:117], s[58:59], v[132:133] op_sel_hi:[1,0,0]
	v_mov_b32_e32 v151, v148
	v_mul_f32_e32 v118, 0x4b800000, v117
	v_cmp_gt_f32_e64 s[42:43], s33, v117
	v_cmp_gt_f32_e32 vcc, s33, v116
	v_mov_b32_e32 v147, v149
	v_cndmask_b32_e64 v117, v117, v118, s[42:43]
	v_rsq_f32_e32 v117, v117
	v_mov_b32_e32 v148, v130
	v_mov_b32_e32 v149, v128
	v_mov_b32_e32 v128, v131
	v_mul_f32_e32 v118, 0x45800000, v117
	v_cndmask_b32_e64 v118, v117, v118, s[42:43]
	v_mul_f32_e32 v117, 0x4b800000, v116
	v_mov_b32_e32 v130, v125
	v_mov_b32_e32 v131, v126
	v_mov_b32_e32 v125, v127
	v_cndmask_b32_e32 v116, v116, v117, vcc
	v_pk_add_f32 v[146:147], v[150:151], v[146:147]
	v_pk_add_f32 v[124:125], v[130:131], v[124:125]
	v_mov_b32_e32 v126, v122
	v_mov_b32_e32 v127, v120
	v_mov_b32_e32 v120, v123
	v_rsq_f32_e32 v116, v116
	v_pk_add_f32 v[128:129], v[148:149], v[128:129]
	v_pk_add_f32 v[120:121], v[126:127], v[120:121]
	v_mov_b32_e32 v122, v124
	v_mov_b32_e32 v123, v146
	v_mov_b32_e32 v146, v125
	v_pk_add_f32 v[122:123], v[122:123], v[146:147]
	v_mov_b32_e32 v124, v121
	v_mov_b32_e32 v125, v129
	v_pk_add_f32 v[122:123], v[122:123], v[124:125]
	v_mov_b32_e32 v121, v128
	v_pk_add_f32 v[120:121], v[120:121], v[122:123]
	v_mul_f32_e32 v117, 0x45800000, v116
	v_pk_fma_f32 v[120:121], v[120:121], s[58:59], v[132:133] op_sel_hi:[1,0,0]
	v_cndmask_b32_e32 v116, v116, v117, vcc
	v_mul_f32_e32 v117, 0x4b800000, v121
	v_cmp_gt_f32_e64 s[42:43], s33, v121
	v_cmp_gt_f32_e32 vcc, s33, v120
	v_mov_b32_e32 v124, v112
	v_cndmask_b32_e64 v117, v121, v117, s[42:43]
	v_rsq_f32_e32 v117, v117
	v_mov_b32_e32 v125, v108
	v_mul_f32_e32 v119, 0x45800000, v117
	v_cndmask_b32_e64 v122, v117, v119, s[42:43]
	v_mul_f32_e32 v117, 0x4b800000, v120
	v_cndmask_b32_e32 v117, v120, v117, vcc
	v_rsq_f32_e32 v117, v117
	s_nop 0
	v_mul_f32_e32 v119, 0x45800000, v117
	v_cndmask_b32_e32 v120, v117, v119, vcc
	v_bitop3_b32 v117, v136, s12, 32 bitop3:0xc8
	v_or_b32_e32 v117, s40, v117
	v_pk_mul_f32 v[118:119], v[124:125], v[118:119] op_sel_hi:[1,0]
	s_nop 0
	v_cvt_pk_bf16_f32 v108, v118, v119
	v_mad_u64_u32 v[118:119], s[12:13], v117, s69, v[134:135]
	v_mad_i32_i24 v119, s41, v207, v119
	global_store_dword v[118:119], v108, off
	v_mov_b32_e32 v108, v113
	v_pk_mul_f32 v[108:109], v[108:109], v[116:117] op_sel_hi:[1,0]
	s_movk_i32 s12, 0xffc
	v_cvt_pk_bf16_f32 v108, v108, v109
	global_store_dword v[118:119], v108, off offset:384
	v_mov_b32_e32 v108, v114
	v_mov_b32_e32 v109, v110
	v_pk_mul_f32 v[108:109], v[108:109], v[122:123] op_sel_hi:[1,0]
	v_mov_b32_e32 v110, v115
	v_cvt_pk_bf16_f32 v108, v108, v109
	global_store_dword v[118:119], v108, off offset:768
	v_pk_mul_f32 v[108:109], v[110:111], v[120:121] op_sel_hi:[1,0]
	s_nop 0
	v_cvt_pk_bf16_f32 v108, v108, v109
	global_store_dword v[118:119], v108, off offset:1152
	v_or_b32_e32 v108, 48, v136
	v_ashrrev_i32_e32 v109, 31, v108
	v_lshlrev_b64 v[108:109], 5, v[108:109]
	v_lshl_add_u64 v[120:121], s[48:49], 0, v[108:109]
	global_load_dwordx4 v[108:111], v[120:121], off offset:48
	global_load_dwordx4 v[112:115], v[120:121], off offset:32
	global_load_dwordx4 v[116:119], v[120:121], off offset:16
	s_nop 0
	global_load_dwordx4 v[120:123], v[120:121], off
	s_waitcnt vmcnt(0)
	v_mov_b32_e32 v124, v121
	v_mov_b32_e32 v125, v122
	v_mov_b32_e32 v121, v123
	v_mov_b32_e32 v122, v118
	v_mov_b32_e32 v123, v116
	v_mov_b32_e32 v116, v119
	v_mov_b32_e32 v118, v113
	v_mov_b32_e32 v119, v114
	v_mov_b32_e32 v113, v115
	v_pk_add_f32 v[120:121], v[124:125], v[120:121]
	v_pk_add_f32 v[112:113], v[118:119], v[112:113]
	v_mov_b32_e32 v114, v110
	v_mov_b32_e32 v115, v108
	v_mov_b32_e32 v108, v111
	v_pk_add_f32 v[116:117], v[122:123], v[116:117]
	v_pk_add_f32 v[108:109], v[114:115], v[108:109]
	v_mov_b32_e32 v110, v112
	v_mov_b32_e32 v111, v120
	v_mov_b32_e32 v120, v113
	v_pk_add_f32 v[110:111], v[110:111], v[120:121]
	v_mov_b32_e32 v112, v109
	v_mov_b32_e32 v113, v117
	v_pk_add_f32 v[110:111], v[110:111], v[112:113]
	v_or_b32_e32 v112, 50, v136
	v_ashrrev_i32_e32 v113, 31, v112
	v_lshlrev_b64 v[112:113], 5, v[112:113]
	v_lshl_add_u64 v[124:125], s[48:49], 0, v[112:113]
	v_mov_b32_e32 v109, v116
	global_load_dwordx4 v[112:115], v[124:125], off offset:48
	global_load_dwordx4 v[116:119], v[124:125], off offset:32
	global_load_dwordx4 v[120:123], v[124:125], off offset:16
	s_nop 0
	global_load_dwordx4 v[124:127], v[124:125], off
	v_pk_add_f32 v[108:109], v[108:109], v[110:111]
	s_waitcnt vmcnt(0)
; #define GAS __attribute__((address_space(1)))
; __device__ __forceinline__ unsigned cvtpk(float lo, float hi) { return __builtin_bit_cast(unsigned, __builtin_convertvector(f32x2_cv{lo, hi}, bf16x2_cv)); }
; __device__ __forceinline__ float rstd_from_ssq(const float* __restrict__ ssq, int row) {
;     const f32x4 a = *(const GAS f32x4*)(ssq + (size_t)row * 8), c = *(const GAS f32x4*)(ssq + (size_t)row * 8 + 4);
;     return rsqrtf(((a[0] + a[1]) + (a[2] + a[3]) + (c[0] + c[1]) + (c[2] + c[3])) * (1.f / 512.f) + RMS_EPS);
; }
;     __device__ __forceinline__ void operator()(const f32x4 (&acc)[2][2][4][2], int brow, int bcol, int wr, int wc, int fr, int fq) const {
;     ...
;                 const int row0 = brow + ai * 128 + wr * 64 + m * 16 + fq * 4, s0 = row0 & 4095;
;                 float rs[4];
; #pragma unroll
;                 for (int j = 0; j < 4; ++j) rs[j] = rstd_from_ssq(ssq, row0 + j);
; #pragma unroll
;                 for (int j = 0; j < 4; ++j)
;                     *(GAS unsigned*)(km + ((size_t)(b * 8 + head) * S + s0 + j) * 192 + wc * 32 + 2 * fr) = cvtpk(acc[ai][0][m][0][j] * rs[j], acc[ai][0][m][1][j] * rs[j]);
	v_mov_b32_e32 v128, v125
	v_pk_fma_f32 v[108:109], v[108:109], s[58:59], v[132:133] op_sel_hi:[1,0,0]
	v_mov_b32_e32 v129, v126
	v_mul_f32_e32 v110, 0x4b800000, v109
	v_cmp_gt_f32_e64 s[42:43], s33, v109
	v_cmp_gt_f32_e32 vcc, s33, v108
	v_mov_b32_e32 v125, v127
	v_cndmask_b32_e64 v109, v109, v110, s[42:43]
	v_rsq_f32_e32 v109, v109
	v_mov_b32_e32 v126, v122
	v_mov_b32_e32 v127, v120
	v_mov_b32_e32 v120, v123
	v_mul_f32_e32 v110, 0x45800000, v109
	v_cndmask_b32_e64 v110, v109, v110, s[42:43]
	v_mul_f32_e32 v109, 0x4b800000, v108
	v_mov_b32_e32 v122, v117
	v_mov_b32_e32 v123, v118
	v_mov_b32_e32 v117, v119
	v_cndmask_b32_e32 v108, v108, v109, vcc
	v_pk_add_f32 v[124:125], v[128:129], v[124:125]
	v_pk_add_f32 v[116:117], v[122:123], v[116:117]
	v_mov_b32_e32 v118, v114
	v_mov_b32_e32 v119, v112
	v_mov_b32_e32 v112, v115
	v_rsq_f32_e32 v108, v108
	v_pk_add_f32 v[120:121], v[126:127], v[120:121]
	v_pk_add_f32 v[112:113], v[118:119], v[112:113]
	v_mov_b32_e32 v114, v116
	v_mov_b32_e32 v115, v124
	v_mov_b32_e32 v124, v117
	v_pk_add_f32 v[114:115], v[114:115], v[124:125]
	v_mov_b32_e32 v116, v113
	v_mov_b32_e32 v117, v121
	v_pk_add_f32 v[114:115], v[114:115], v[116:117]
	v_mov_b32_e32 v113, v120
	v_pk_add_f32 v[112:113], v[112:113], v[114:115]
	v_mul_f32_e32 v109, 0x45800000, v108
	v_pk_fma_f32 v[112:113], v[112:113], s[58:59], v[132:133] op_sel_hi:[1,0,0]
	v_cndmask_b32_e32 v108, v108, v109, vcc
	v_mul_f32_e32 v109, 0x4b800000, v113
	v_cmp_gt_f32_e64 s[42:43], s33, v113
	v_cmp_gt_f32_e32 vcc, s33, v112
	v_mov_b32_e32 v116, v104
	v_cndmask_b32_e64 v109, v113, v109, s[42:43]
	v_rsq_f32_e32 v109, v109
	v_mov_b32_e32 v117, v100
	v_mul_f32_e32 v111, 0x45800000, v109
	v_cndmask_b32_e64 v114, v109, v111, s[42:43]
	v_mul_f32_e32 v109, 0x4b800000, v112
	v_cndmask_b32_e32 v109, v112, v109, vcc
	v_rsq_f32_e32 v109, v109
	s_nop 0
	v_mul_f32_e32 v111, 0x45800000, v109
	v_cndmask_b32_e32 v112, v109, v111, vcc
	v_bitop3_b32 v109, v136, s12, 48 bitop3:0xc8
	v_or_b32_e32 v109, s40, v109
	v_pk_mul_f32 v[110:111], v[116:117], v[110:111] op_sel_hi:[1,0]
	s_nop 0
	v_cvt_pk_bf16_f32 v100, v110, v111
	v_mad_u64_u32 v[110:111], s[12:13], v109, s69, v[134:135]
	v_mad_i32_i24 v111, s41, v207, v111
	global_store_dword v[110:111], v100, off
	v_mov_b32_e32 v100, v105
	v_pk_mul_f32 v[100:101], v[100:101], v[108:109] op_sel_hi:[1,0]
	s_nop 0
	v_cvt_pk_bf16_f32 v100, v100, v101
	global_store_dword v[110:111], v100, off offset:384
	v_mov_b32_e32 v100, v106
	v_mov_b32_e32 v101, v102
	v_pk_mul_f32 v[100:101], v[100:101], v[114:115] op_sel_hi:[1,0]
	v_mov_b32_e32 v102, v107
	v_cvt_pk_bf16_f32 v100, v100, v101
	global_store_dword v[110:111], v100, off offset:768
	v_pk_mul_f32 v[100:101], v[102:103], v[112:113] op_sel_hi:[1,0]
	s_nop 0
	v_cvt_pk_bf16_f32 v100, v100, v101
	global_store_dword v[110:111], v100, off offset:1152
	v_add_u32_e32 v100, 0x80, v136
	v_ashrrev_i32_e32 v101, 31, v100
	v_lshlrev_b64 v[102:103], 5, v[100:101]
	v_lshl_add_u64 v[114:115], s[48:49], 0, v[102:103]
	global_load_dwordx4 v[102:105], v[114:115], off offset:48
	global_load_dwordx4 v[106:109], v[114:115], off offset:32
	global_load_dwordx4 v[110:113], v[114:115], off offset:16
	s_nop 0
	global_load_dwordx4 v[114:117], v[114:115], off
	v_and_b32_e32 v100, 0xfcc, v100
	s_waitcnt vmcnt(0)
	v_mov_b32_e32 v118, v115
	v_mov_b32_e32 v119, v116
	v_mov_b32_e32 v115, v117
	v_mov_b32_e32 v116, v112
	v_mov_b32_e32 v117, v110
	v_mov_b32_e32 v110, v113
	v_mov_b32_e32 v112, v107
	v_mov_b32_e32 v113, v108
	v_mov_b32_e32 v107, v109
	v_pk_add_f32 v[114:115], v[118:119], v[114:115]
	v_pk_add_f32 v[106:107], v[112:113], v[106:107]
	v_mov_b32_e32 v108, v104
	v_mov_b32_e32 v109, v102
	v_mov_b32_e32 v102, v105
	v_pk_add_f32 v[110:111], v[116:117], v[110:111]
	v_pk_add_f32 v[102:103], v[108:109], v[102:103]
	v_mov_b32_e32 v104, v106
	v_mov_b32_e32 v105, v114
	v_mov_b32_e32 v114, v107
	v_pk_add_f32 v[104:105], v[104:105], v[114:115]
	v_mov_b32_e32 v106, v103
	v_mov_b32_e32 v107, v111
	v_pk_add_f32 v[104:105], v[104:105], v[106:107]
	v_add_u32_e32 v106, 0x82, v136
	v_ashrrev_i32_e32 v107, 31, v106
	v_lshlrev_b64 v[106:107], 5, v[106:107]
	v_lshl_add_u64 v[118:119], s[48:49], 0, v[106:107]
	v_mov_b32_e32 v103, v110
	global_load_dwordx4 v[106:109], v[118:119], off offset:48
	global_load_dwordx4 v[110:113], v[118:119], off offset:32
	global_load_dwordx4 v[114:117], v[118:119], off offset:16
	s_nop 0
	global_load_dwordx4 v[118:121], v[118:119], off
	v_pk_add_f32 v[102:103], v[102:103], v[104:105]
	s_waitcnt vmcnt(0)
; #define GAS __attribute__((address_space(1)))
; __device__ __forceinline__ unsigned cvtpk(float lo, float hi) { return __builtin_bit_cast(unsigned, __builtin_convertvector(f32x2_cv{lo, hi}, bf16x2_cv)); }
; __device__ __forceinline__ float rstd_from_ssq(const float* __restrict__ ssq, int row) {
;     const f32x4 a = *(const GAS f32x4*)(ssq + (size_t)row * 8), c = *(const GAS f32x4*)(ssq + (size_t)row * 8 + 4);
;     return rsqrtf(((a[0] + a[1]) + (a[2] + a[3]) + (c[0] + c[1]) + (c[2] + c[3])) * (1.f / 512.f) + RMS_EPS);
; }
;     __device__ __forceinline__ void operator()(const f32x4 (&acc)[2][2][4][2], int brow, int bcol, int wr, int wc, int fr, int fq) const {
;     ...
;                 const int row0 = brow + ai * 128 + wr * 64 + m * 16 + fq * 4, s0 = row0 & 4095;
;                 float rs[4];
; #pragma unroll
;                 for (int j = 0; j < 4; ++j) rs[j] = rstd_from_ssq(ssq, row0 + j);
; #pragma unroll
;                 for (int j = 0; j < 4; ++j)
;                     *(GAS unsigned*)(km + ((size_t)(b * 8 + head) * S + s0 + j) * 192 + wc * 32 + 2 * fr) = cvtpk(acc[ai][0][m][0][j] * rs[j], acc[ai][0][m][1][j] * rs[j]);
	v_mov_b32_e32 v122, v119
	v_pk_fma_f32 v[102:103], v[102:103], s[58:59], v[132:133] op_sel_hi:[1,0,0]
	v_mov_b32_e32 v123, v120
	v_mul_f32_e32 v101, 0x4b800000, v103
	v_cmp_gt_f32_e64 s[42:43], s33, v103
	v_cmp_gt_f32_e32 vcc, s33, v102
	v_mov_b32_e32 v119, v121
	v_cndmask_b32_e64 v101, v103, v101, s[42:43]
	v_rsq_f32_e32 v101, v101
	v_mov_b32_e32 v120, v116
	v_mov_b32_e32 v121, v114
	v_mov_b32_e32 v114, v117
	v_mul_f32_e32 v103, 0x45800000, v101
	v_cndmask_b32_e64 v104, v101, v103, s[42:43]
	v_mul_f32_e32 v101, 0x4b800000, v102
	v_mov_b32_e32 v116, v111
	v_mov_b32_e32 v117, v112
	v_mov_b32_e32 v111, v113
	v_cndmask_b32_e32 v101, v102, v101, vcc
	v_pk_add_f32 v[118:119], v[122:123], v[118:119]
	v_pk_add_f32 v[110:111], v[116:117], v[110:111]
	v_mov_b32_e32 v112, v108
	v_mov_b32_e32 v113, v106
	v_mov_b32_e32 v106, v109
	v_rsq_f32_e32 v101, v101
	v_pk_add_f32 v[114:115], v[120:121], v[114:115]
	v_pk_add_f32 v[106:107], v[112:113], v[106:107]
	v_mov_b32_e32 v108, v110
	v_mov_b32_e32 v109, v118
	v_mov_b32_e32 v118, v111
	v_pk_add_f32 v[108:109], v[108:109], v[118:119]
	v_mov_b32_e32 v110, v107
	v_mov_b32_e32 v111, v115
	v_pk_add_f32 v[108:109], v[108:109], v[110:111]
	v_mov_b32_e32 v107, v114
	v_pk_add_f32 v[106:107], v[106:107], v[108:109]
	v_mul_f32_e32 v102, 0x45800000, v101
	v_pk_fma_f32 v[106:107], v[106:107], s[58:59], v[132:133] op_sel_hi:[1,0,0]
	v_cndmask_b32_e32 v102, v101, v102, vcc
	v_mul_f32_e32 v101, 0x4b800000, v107
	v_cmp_gt_f32_e64 s[42:43], s33, v107
	v_cmp_gt_f32_e32 vcc, s33, v106
	s_nop 0
	v_cndmask_b32_e64 v101, v107, v101, s[42:43]
	v_rsq_f32_e32 v101, v101
	s_nop 0
	v_mul_f32_e32 v103, 0x45800000, v101
	v_cndmask_b32_e64 v108, v101, v103, s[42:43]
	v_mul_f32_e32 v101, 0x4b800000, v106
	v_cndmask_b32_e32 v101, v106, v101, vcc
	v_rsq_f32_e32 v101, v101
	s_nop 0
	v_mul_f32_e32 v103, 0x45800000, v101
	v_cndmask_b32_e32 v106, v101, v103, vcc
	v_or_b32_e32 v103, s40, v100
	v_mov_b32_e32 v100, v96
	v_mov_b32_e32 v101, v92
	v_pk_mul_f32 v[100:101], v[100:101], v[104:105] op_sel_hi:[1,0]
	s_nop 0
	v_cvt_pk_bf16_f32 v92, v100, v101
	v_mad_u64_u32 v[100:101], s[12:13], v103, s69, v[134:135]
	v_mad_i32_i24 v101, s41, v207, v101
	global_store_dword v[100:101], v92, off
	v_mov_b32_e32 v92, v97
	v_pk_mul_f32 v[92:93], v[92:93], v[102:103] op_sel_hi:[1,0]
	s_nop 0
	v_cvt_pk_bf16_f32 v92, v92, v93
	global_store_dword v[100:101], v92, off offset:384
	v_mov_b32_e32 v92, v98
	v_mov_b32_e32 v93, v94
	v_pk_mul_f32 v[92:93], v[92:93], v[108:109] op_sel_hi:[1,0]
	v_mov_b32_e32 v94, v99
	v_cvt_pk_bf16_f32 v92, v92, v93
	global_store_dword v[100:101], v92, off offset:768
	v_pk_mul_f32 v[92:93], v[94:95], v[106:107] op_sel_hi:[1,0]
	s_nop 0
	v_cvt_pk_bf16_f32 v92, v92, v93
	global_store_dword v[100:101], v92, off offset:1152
	v_add_u32_e32 v92, 0x90, v136
	v_ashrrev_i32_e32 v93, 31, v92
	v_lshlrev_b64 v[94:95], 5, v[92:93]
	v_lshl_add_u64 v[106:107], s[48:49], 0, v[94:95]
	global_load_dwordx4 v[94:97], v[106:107], off offset:48
	global_load_dwordx4 v[98:101], v[106:107], off offset:32
	global_load_dwordx4 v[102:105], v[106:107], off offset:16
	s_nop 0
	global_load_dwordx4 v[106:109], v[106:107], off
	v_and_b32_e32 v92, 0xfdc, v92
	s_waitcnt vmcnt(0)
	v_mov_b32_e32 v110, v107
	v_mov_b32_e32 v111, v108
	v_mov_b32_e32 v107, v109
	v_mov_b32_e32 v108, v104
	v_mov_b32_e32 v109, v102
	v_mov_b32_e32 v102, v105
	v_mov_b32_e32 v104, v99
	v_mov_b32_e32 v105, v100
	v_mov_b32_e32 v99, v101
	v_pk_add_f32 v[106:107], v[110:111], v[106:107]
	v_pk_add_f32 v[98:99], v[104:105], v[98:99]
	v_mov_b32_e32 v100, v96
	v_mov_b32_e32 v101, v94
	v_mov_b32_e32 v94, v97
	v_pk_add_f32 v[102:103], v[108:109], v[102:103]
	v_pk_add_f32 v[94:95], v[100:101], v[94:95]
	v_mov_b32_e32 v96, v98
	v_mov_b32_e32 v97, v106
	v_mov_b32_e32 v106, v99
	v_pk_add_f32 v[96:97], v[96:97], v[106:107]
	v_mov_b32_e32 v98, v95
	v_mov_b32_e32 v99, v103
	v_pk_add_f32 v[96:97], v[96:97], v[98:99]
	v_add_u32_e32 v98, 0x92, v136
	v_ashrrev_i32_e32 v99, 31, v98
	v_lshlrev_b64 v[98:99], 5, v[98:99]
	v_lshl_add_u64 v[110:111], s[48:49], 0, v[98:99]
	v_mov_b32_e32 v95, v102
	global_load_dwordx4 v[98:101], v[110:111], off offset:48
	global_load_dwordx4 v[102:105], v[110:111], off offset:32
	global_load_dwordx4 v[106:109], v[110:111], off offset:16
	s_nop 0
	global_load_dwordx4 v[110:113], v[110:111], off
	v_pk_add_f32 v[94:95], v[94:95], v[96:97]
	s_waitcnt vmcnt(0)
; #define GAS __attribute__((address_space(1)))
; __device__ __forceinline__ unsigned cvtpk(float lo, float hi) { return __builtin_bit_cast(unsigned, __builtin_convertvector(f32x2_cv{lo, hi}, bf16x2_cv)); }
; __device__ __forceinline__ float rstd_from_ssq(const float* __restrict__ ssq, int row) {
;     const f32x4 a = *(const GAS f32x4*)(ssq + (size_t)row * 8), c = *(const GAS f32x4*)(ssq + (size_t)row * 8 + 4);
;     return rsqrtf(((a[0] + a[1]) + (a[2] + a[3]) + (c[0] + c[1]) + (c[2] + c[3])) * (1.f / 512.f) + RMS_EPS);
; }
;     __device__ __forceinline__ void operator()(const f32x4 (&acc)[2][2][4][2], int brow, int bcol, int wr, int wc, int fr, int fq) const {
;     ...
;                 const int row0 = brow + ai * 128 + wr * 64 + m * 16 + fq * 4, s0 = row0 & 4095;
;                 float rs[4];
; #pragma unroll
;                 for (int j = 0; j < 4; ++j) rs[j] = rstd_from_ssq(ssq, row0 + j);
; #pragma unroll
;                 for (int j = 0; j < 4; ++j)
;                     *(GAS unsigned*)(km + ((size_t)(b * 8 + head) * S + s0 + j) * 192 + wc * 32 + 2 * fr) = cvtpk(acc[ai][0][m][0][j] * rs[j], acc[ai][0][m][1][j] * rs[j]);
	v_mov_b32_e32 v114, v111
	v_pk_fma_f32 v[94:95], v[94:95], s[58:59], v[132:133] op_sel_hi:[1,0,0]
	v_mov_b32_e32 v115, v112
	v_mul_f32_e32 v93, 0x4b800000, v95
	v_cmp_gt_f32_e64 s[42:43], s33, v95
	v_cmp_gt_f32_e32 vcc, s33, v94
	v_mov_b32_e32 v111, v113
	v_cndmask_b32_e64 v93, v95, v93, s[42:43]
	v_rsq_f32_e32 v93, v93
	v_mov_b32_e32 v112, v108
	v_mov_b32_e32 v113, v106
	v_mov_b32_e32 v106, v109
	v_mul_f32_e32 v95, 0x45800000, v93
	v_cndmask_b32_e64 v96, v93, v95, s[42:43]
	v_mul_f32_e32 v93, 0x4b800000, v94
	v_mov_b32_e32 v108, v103
	v_mov_b32_e32 v109, v104
	v_mov_b32_e32 v103, v105
	v_cndmask_b32_e32 v93, v94, v93, vcc
	v_pk_add_f32 v[110:111], v[114:115], v[110:111]
	v_pk_add_f32 v[102:103], v[108:109], v[102:103]
	v_mov_b32_e32 v104, v100
	v_mov_b32_e32 v105, v98
	v_mov_b32_e32 v98, v101
	v_rsq_f32_e32 v93, v93
	v_pk_add_f32 v[106:107], v[112:113], v[106:107]
	v_pk_add_f32 v[98:99], v[104:105], v[98:99]
	v_mov_b32_e32 v100, v102
	v_mov_b32_e32 v101, v110
	v_mov_b32_e32 v110, v103
	v_pk_add_f32 v[100:101], v[100:101], v[110:111]
	v_mov_b32_e32 v102, v99
	v_mov_b32_e32 v103, v107
	v_pk_add_f32 v[100:101], v[100:101], v[102:103]
	v_mov_b32_e32 v99, v106
	v_pk_add_f32 v[98:99], v[98:99], v[100:101]
	v_mul_f32_e32 v94, 0x45800000, v93
	v_pk_fma_f32 v[98:99], v[98:99], s[58:59], v[132:133] op_sel_hi:[1,0,0]
	v_cndmask_b32_e32 v94, v93, v94, vcc
	v_mul_f32_e32 v93, 0x4b800000, v99
	v_cmp_gt_f32_e64 s[42:43], s33, v99
	v_cmp_gt_f32_e32 vcc, s33, v98
	s_nop 0
	v_cndmask_b32_e64 v93, v99, v93, s[42:43]
	v_rsq_f32_e32 v93, v93
	s_nop 0
	v_mul_f32_e32 v95, 0x45800000, v93
	v_cndmask_b32_e64 v100, v93, v95, s[42:43]
	v_mul_f32_e32 v93, 0x4b800000, v98
	v_cndmask_b32_e32 v93, v98, v93, vcc
	v_rsq_f32_e32 v93, v93
	s_nop 0
	v_mul_f32_e32 v95, 0x45800000, v93
	v_cndmask_b32_e32 v98, v93, v95, vcc
	v_or_b32_e32 v95, s40, v92
	v_mov_b32_e32 v92, v88
	v_mov_b32_e32 v93, v84
	v_pk_mul_f32 v[92:93], v[92:93], v[96:97] op_sel_hi:[1,0]
	s_nop 0
	v_cvt_pk_bf16_f32 v84, v92, v93
	v_mad_u64_u32 v[92:93], s[12:13], v95, s69, v[134:135]
	v_mad_i32_i24 v93, s41, v207, v93
	global_store_dword v[92:93], v84, off
	v_mov_b32_e32 v84, v89
	v_pk_mul_f32 v[84:85], v[84:85], v[94:95] op_sel_hi:[1,0]
	s_nop 0
	v_cvt_pk_bf16_f32 v84, v84, v85
	global_store_dword v[92:93], v84, off offset:384
	v_mov_b32_e32 v84, v90
	v_mov_b32_e32 v85, v86
	v_pk_mul_f32 v[84:85], v[84:85], v[100:101] op_sel_hi:[1,0]
	v_mov_b32_e32 v86, v91
	v_cvt_pk_bf16_f32 v84, v84, v85
	global_store_dword v[92:93], v84, off offset:768
	v_pk_mul_f32 v[84:85], v[86:87], v[98:99] op_sel_hi:[1,0]
	s_nop 0
	v_cvt_pk_bf16_f32 v84, v84, v85
	global_store_dword v[92:93], v84, off offset:1152
	v_add_u32_e32 v84, 0xa0, v136
	v_ashrrev_i32_e32 v85, 31, v84
	v_lshlrev_b64 v[86:87], 5, v[84:85]
	v_lshl_add_u64 v[98:99], s[48:49], 0, v[86:87]
	global_load_dwordx4 v[86:89], v[98:99], off offset:48
	global_load_dwordx4 v[90:93], v[98:99], off offset:32
	global_load_dwordx4 v[94:97], v[98:99], off offset:16
	s_nop 0
	global_load_dwordx4 v[98:101], v[98:99], off
	v_and_b32_e32 v84, 0xfec, v84
	s_waitcnt vmcnt(0)
	v_mov_b32_e32 v102, v99
	v_mov_b32_e32 v103, v100
	v_mov_b32_e32 v99, v101
	v_mov_b32_e32 v100, v96
	v_mov_b32_e32 v101, v94
	v_mov_b32_e32 v94, v97
	v_mov_b32_e32 v96, v91
	v_mov_b32_e32 v97, v92
	v_mov_b32_e32 v91, v93
	v_pk_add_f32 v[98:99], v[102:103], v[98:99]
	v_pk_add_f32 v[90:91], v[96:97], v[90:91]
	v_mov_b32_e32 v92, v88
	v_mov_b32_e32 v93, v86
	v_mov_b32_e32 v86, v89
	v_pk_add_f32 v[94:95], v[100:101], v[94:95]
	v_pk_add_f32 v[86:87], v[92:93], v[86:87]
	v_mov_b32_e32 v88, v90
	v_mov_b32_e32 v89, v98
	v_mov_b32_e32 v98, v91
	v_pk_add_f32 v[88:89], v[88:89], v[98:99]
	v_mov_b32_e32 v90, v87
	v_mov_b32_e32 v91, v95
	v_pk_add_f32 v[88:89], v[88:89], v[90:91]
	v_add_u32_e32 v90, 0xa2, v136
	v_ashrrev_i32_e32 v91, 31, v90
	v_lshlrev_b64 v[90:91], 5, v[90:91]
	v_lshl_add_u64 v[102:103], s[48:49], 0, v[90:91]
	v_mov_b32_e32 v87, v94
	global_load_dwordx4 v[90:93], v[102:103], off offset:48
	global_load_dwordx4 v[94:97], v[102:103], off offset:32
	global_load_dwordx4 v[98:101], v[102:103], off offset:16
	s_nop 0
	global_load_dwordx4 v[102:105], v[102:103], off
	v_pk_add_f32 v[86:87], v[86:87], v[88:89]
	s_waitcnt vmcnt(0)
; #define GAS __attribute__((address_space(1)))
; __device__ __forceinline__ unsigned cvtpk(float lo, float hi) { return __builtin_bit_cast(unsigned, __builtin_convertvector(f32x2_cv{lo, hi}, bf16x2_cv)); }
; __device__ __forceinline__ float rstd_from_ssq(const float* __restrict__ ssq, int row) {
;     const f32x4 a = *(const GAS f32x4*)(ssq + (size_t)row * 8), c = *(const GAS f32x4*)(ssq + (size_t)row * 8 + 4);
;     return rsqrtf(((a[0] + a[1]) + (a[2] + a[3]) + (c[0] + c[1]) + (c[2] + c[3])) * (1.f / 512.f) + RMS_EPS);
; }
;     __device__ __forceinline__ void operator()(const f32x4 (&acc)[2][2][4][2], int brow, int bcol, int wr, int wc, int fr, int fq) const {
;     ...
;                 const int row0 = brow + ai * 128 + wr * 64 + m * 16 + fq * 4, s0 = row0 & 4095;
;                 float rs[4];
; #pragma unroll
;                 for (int j = 0; j < 4; ++j) rs[j] = rstd_from_ssq(ssq, row0 + j);
; #pragma unroll
;                 for (int j = 0; j < 4; ++j)
;                     *(GAS unsigned*)(km + ((size_t)(b * 8 + head) * S + s0 + j) * 192 + wc * 32 + 2 * fr) = cvtpk(acc[ai][0][m][0][j] * rs[j], acc[ai][0][m][1][j] * rs[j]);
	v_mov_b32_e32 v106, v103
	v_pk_fma_f32 v[86:87], v[86:87], s[58:59], v[132:133] op_sel_hi:[1,0,0]
	v_mov_b32_e32 v107, v104
	v_mul_f32_e32 v85, 0x4b800000, v87
	v_cmp_gt_f32_e64 s[42:43], s33, v87
	v_cmp_gt_f32_e32 vcc, s33, v86
	v_mov_b32_e32 v103, v105
	v_cndmask_b32_e64 v85, v87, v85, s[42:43]
	v_rsq_f32_e32 v85, v85
	v_mov_b32_e32 v104, v100
	v_mov_b32_e32 v105, v98
	v_mov_b32_e32 v98, v101
	v_mul_f32_e32 v87, 0x45800000, v85
	v_cndmask_b32_e64 v88, v85, v87, s[42:43]
	v_mul_f32_e32 v85, 0x4b800000, v86
	v_mov_b32_e32 v100, v95
	v_mov_b32_e32 v101, v96
	v_mov_b32_e32 v95, v97
	v_cndmask_b32_e32 v85, v86, v85, vcc
	v_pk_add_f32 v[102:103], v[106:107], v[102:103]
	v_pk_add_f32 v[94:95], v[100:101], v[94:95]
	v_mov_b32_e32 v96, v92
	v_mov_b32_e32 v97, v90
	v_mov_b32_e32 v90, v93
	v_rsq_f32_e32 v85, v85
	v_pk_add_f32 v[98:99], v[104:105], v[98:99]
	v_pk_add_f32 v[90:91], v[96:97], v[90:91]
	v_mov_b32_e32 v92, v94
	v_mov_b32_e32 v93, v102
	v_mov_b32_e32 v102, v95
	v_pk_add_f32 v[92:93], v[92:93], v[102:103]
	v_mov_b32_e32 v94, v91
	v_mov_b32_e32 v95, v99
	v_pk_add_f32 v[92:93], v[92:93], v[94:95]
	v_mov_b32_e32 v91, v98
	v_pk_add_f32 v[90:91], v[90:91], v[92:93]
	v_mul_f32_e32 v86, 0x45800000, v85
	v_pk_fma_f32 v[90:91], v[90:91], s[58:59], v[132:133] op_sel_hi:[1,0,0]
	v_cndmask_b32_e32 v86, v85, v86, vcc
	v_mul_f32_e32 v85, 0x4b800000, v91
	v_cmp_gt_f32_e64 s[42:43], s33, v91
	v_cmp_gt_f32_e32 vcc, s33, v90
	s_nop 0
	v_cndmask_b32_e64 v85, v91, v85, s[42:43]
	v_rsq_f32_e32 v85, v85
	s_nop 0
	v_mul_f32_e32 v87, 0x45800000, v85
	v_cndmask_b32_e64 v92, v85, v87, s[42:43]
	v_mul_f32_e32 v85, 0x4b800000, v90
	v_cndmask_b32_e32 v85, v90, v85, vcc
	v_rsq_f32_e32 v85, v85
	s_nop 0
	v_mul_f32_e32 v87, 0x45800000, v85
	v_cndmask_b32_e32 v90, v85, v87, vcc
	v_or_b32_e32 v87, s40, v84
	v_mov_b32_e32 v84, v80
	v_mov_b32_e32 v85, v76
	v_pk_mul_f32 v[84:85], v[84:85], v[88:89] op_sel_hi:[1,0]
	s_nop 0
	v_cvt_pk_bf16_f32 v76, v84, v85
	v_mad_u64_u32 v[84:85], s[12:13], v87, s69, v[134:135]
	v_mad_i32_i24 v85, s41, v207, v85
	global_store_dword v[84:85], v76, off
	v_mov_b32_e32 v76, v81
	v_pk_mul_f32 v[76:77], v[76:77], v[86:87] op_sel_hi:[1,0]
	s_nop 0
	v_cvt_pk_bf16_f32 v76, v76, v77
	global_store_dword v[84:85], v76, off offset:384
	v_mov_b32_e32 v76, v82
	v_mov_b32_e32 v77, v78
	v_pk_mul_f32 v[76:77], v[76:77], v[92:93] op_sel_hi:[1,0]
	v_mov_b32_e32 v78, v83
	v_cvt_pk_bf16_f32 v76, v76, v77
	global_store_dword v[84:85], v76, off offset:768
	v_pk_mul_f32 v[76:77], v[78:79], v[90:91] op_sel_hi:[1,0]
	s_nop 0
	v_cvt_pk_bf16_f32 v76, v76, v77
	global_store_dword v[84:85], v76, off offset:1152
	v_add_u32_e32 v76, 0xb0, v136
	v_ashrrev_i32_e32 v77, 31, v76
	v_lshlrev_b64 v[78:79], 5, v[76:77]
	v_lshl_add_u64 v[90:91], s[48:49], 0, v[78:79]
	global_load_dwordx4 v[78:81], v[90:91], off offset:48
	global_load_dwordx4 v[82:85], v[90:91], off offset:32
	global_load_dwordx4 v[86:89], v[90:91], off offset:16
	s_nop 0
	global_load_dwordx4 v[90:93], v[90:91], off
	v_and_b32_e32 v76, 0xffc, v76
	s_waitcnt vmcnt(0)
	v_mov_b32_e32 v94, v91
	v_mov_b32_e32 v95, v92
	v_mov_b32_e32 v91, v93
	v_mov_b32_e32 v92, v88
	v_mov_b32_e32 v93, v86
	v_mov_b32_e32 v86, v89
	v_mov_b32_e32 v88, v83
	v_mov_b32_e32 v89, v84
	v_mov_b32_e32 v83, v85
	v_pk_add_f32 v[90:91], v[94:95], v[90:91]
	v_pk_add_f32 v[82:83], v[88:89], v[82:83]
	v_mov_b32_e32 v84, v80
	v_mov_b32_e32 v85, v78
	v_mov_b32_e32 v78, v81
	v_pk_add_f32 v[86:87], v[92:93], v[86:87]
	v_pk_add_f32 v[78:79], v[84:85], v[78:79]
	v_mov_b32_e32 v80, v82
	v_mov_b32_e32 v81, v90
	v_mov_b32_e32 v90, v83
	v_pk_add_f32 v[80:81], v[80:81], v[90:91]
	v_mov_b32_e32 v82, v79
	v_mov_b32_e32 v83, v87
	v_pk_add_f32 v[80:81], v[80:81], v[82:83]
	v_add_u32_e32 v82, 0xb2, v136
	v_ashrrev_i32_e32 v83, 31, v82
	v_lshlrev_b64 v[82:83], 5, v[82:83]
	v_lshl_add_u64 v[94:95], s[48:49], 0, v[82:83]
	v_mov_b32_e32 v79, v86
	global_load_dwordx4 v[82:85], v[94:95], off offset:48
	global_load_dwordx4 v[86:89], v[94:95], off offset:32
	global_load_dwordx4 v[90:93], v[94:95], off offset:16
	s_nop 0
	global_load_dwordx4 v[94:97], v[94:95], off
	v_pk_add_f32 v[78:79], v[78:79], v[80:81]
	s_waitcnt vmcnt(0)
	v_mov_b32_e32 v98, v95
	v_pk_fma_f32 v[78:79], v[78:79], s[58:59], v[132:133] op_sel_hi:[1,0,0]
	v_mov_b32_e32 v99, v96
	v_mul_f32_e32 v77, 0x4b800000, v79
	v_cmp_gt_f32_e64 s[42:43], s33, v79
	v_cmp_gt_f32_e32 vcc, s33, v78
	v_mov_b32_e32 v95, v97
	v_cndmask_b32_e64 v77, v79, v77, s[42:43]
	v_rsq_f32_e32 v77, v77
	v_mov_b32_e32 v96, v92
	v_mov_b32_e32 v97, v90
	v_mov_b32_e32 v90, v93
	v_mul_f32_e32 v79, 0x45800000, v77
	v_cndmask_b32_e64 v80, v77, v79, s[42:43]
	v_mul_f32_e32 v77, 0x4b800000, v78
	v_mov_b32_e32 v92, v87
	v_mov_b32_e32 v93, v88
	v_mov_b32_e32 v87, v89
	v_cndmask_b32_e32 v77, v78, v77, vcc
	v_pk_add_f32 v[94:95], v[98:99], v[94:95]
	v_pk_add_f32 v[86:87], v[92:93], v[86:87]
	v_mov_b32_e32 v88, v84
	v_mov_b32_e32 v89, v82
	v_mov_b32_e32 v82, v85
	v_rsq_f32_e32 v77, v77
	v_pk_add_f32 v[90:91], v[96:97], v[90:91]
	v_pk_add_f32 v[82:83], v[88:89], v[82:83]
	v_mov_b32_e32 v84, v86
	v_mov_b32_e32 v85, v94
	v_mov_b32_e32 v94, v87
	v_pk_add_f32 v[84:85], v[84:85], v[94:95]
	v_mov_b32_e32 v86, v83
	v_mov_b32_e32 v87, v91
	v_pk_add_f32 v[84:85], v[84:85], v[86:87]
	v_mov_b32_e32 v83, v90
	v_pk_add_f32 v[82:83], v[82:83], v[84:85]
	v_mul_f32_e32 v78, 0x45800000, v77
	v_pk_fma_f32 v[82:83], v[82:83], s[58:59], v[132:133] op_sel_hi:[1,0,0]
	v_cndmask_b32_e32 v78, v77, v78, vcc
	v_mul_f32_e32 v77, 0x4b800000, v83
	v_cmp_gt_f32_e64 s[42:43], s33, v83
	v_cmp_gt_f32_e32 vcc, s33, v82
	s_nop 0
	v_cndmask_b32_e64 v77, v83, v77, s[42:43]
	v_rsq_f32_e32 v77, v77
; #define LAS __attribute__((address_space(3)))
; #define GAS __attribute__((address_space(1)))
; __device__ __forceinline__ unsigned cvtpk(float lo, float hi) { return __builtin_bit_cast(unsigned, __builtin_convertvector(f32x2_cv{lo, hi}, bf16x2_cv)); }
; template <int BJ_LO, int BJ_HI>
; __device__ __forceinline__ void vt_store_lds(const f32x4 (&acc)[2][2][4][2], int brow, int wr, int wc, int fr, int fq, const float* __restrict__ ssq, bf16_t* dst0) {
;     extern __shared__ __attribute__((aligned(16))) unsigned char vt_lds[];
;     constexpr int PITCH = 528;
;     LAS unsigned char* L = (LAS unsigned char*)vt_lds;
; #pragma unroll
;     for (int ai = 0; ai < 2; ++ai)
; #pragma unroll
;         for (int m = 0; m < 4; ++m) {
;             const int r0 = ai * 128 + wr * 64 + m * 16 + fq * 4;
;             float rs[4] = {1.f, 1.f, 1.f, 1.f};
;             if (ssq) {
; #pragma unroll
;                 for (int j = 0; j < 4; ++j) {
;                     const f32x4 a = *(const GAS f32x4*)(ssq + (size_t)(brow + r0 + j) * 8), c = *(const GAS f32x4*)(ssq + (size_t)(brow + r0 + j) * 8 + 4);
;                     rs[j] = rsqrtf(((a[0] + a[1]) + (a[2] + a[3]) + (c[0] + c[1]) + (c[2] + c[3])) * (1.f / 512.f) + RMS_EPS);
;                 }
;             }
; #pragma unroll
;             for (int bj = BJ_LO; bj < BJ_HI; ++bj)
; #pragma unroll
;                 for (int n = 0; n < 2; ++n) {
;                     const f32x4 a = acc[ai][bj][m][n];
;                     const int col = (bj - BJ_LO) * 128 + wc * 32 + n * 16 + fr;
;                     *(LAS u32x2*)(L + col * PITCH + r0 * 2) = u32x2{cvtpk(a[0] * rs[0], a[1] * rs[1]), cvtpk(a[2] * rs[2], a[3] * rs[3])};
;                 }
;         }
;     __device__ __forceinline__ void operator()(const f32x4 (&acc)[2][2][4][2], int brow, int bcol, int wr, int wc, int fr, int fq) const {
;     ...
;                     *(GAS unsigned*)(km + ((size_t)(b * 8 + head) * S + s0 + j) * 192 + wc * 32 + 2 * fr) = cvtpk(acc[ai][0][m][0][j] * rs[j], acc[ai][0][m][1][j] * rs[j]);
	s_nop 0
	v_mul_f32_e32 v79, 0x45800000, v77
	v_cndmask_b32_e64 v84, v77, v79, s[42:43]
	v_mul_f32_e32 v77, 0x4b800000, v82
	v_cndmask_b32_e32 v77, v82, v77, vcc
	v_rsq_f32_e32 v77, v77
	s_nop 0
	v_mul_f32_e32 v79, 0x45800000, v77
	v_cndmask_b32_e32 v82, v77, v79, vcc
	v_or_b32_e32 v79, s40, v76
	v_mov_b32_e32 v76, v72
	v_mov_b32_e32 v77, v68
	v_pk_mul_f32 v[76:77], v[76:77], v[80:81] op_sel_hi:[1,0]
	s_nop 0
	v_cvt_pk_bf16_f32 v68, v76, v77
	v_mad_u64_u32 v[76:77], s[12:13], v79, s69, v[134:135]
	v_mad_i32_i24 v77, s41, v207, v77
	global_store_dword v[76:77], v68, off
	v_mov_b32_e32 v68, v73
	v_pk_mul_f32 v[68:69], v[68:69], v[78:79] op_sel_hi:[1,0]
	s_lshl_b64 s[12:13], s[56:57], 20
	v_cvt_pk_bf16_f32 v68, v68, v69
	global_store_dword v[76:77], v68, off offset:384
	v_mov_b32_e32 v68, v74
	v_mov_b32_e32 v69, v70
	v_pk_mul_f32 v[68:69], v[68:69], v[84:85] op_sel_hi:[1,0]
	v_mov_b32_e32 v70, v75
	v_cvt_pk_bf16_f32 v68, v68, v69
	global_store_dword v[76:77], v68, off offset:768
	v_pk_mul_f32 v[68:69], v[70:71], v[82:83] op_sel_hi:[1,0]
	s_add_u32 s12, s26, s12
	v_cvt_pk_bf16_f32 v68, v68, v69
	global_store_dword v[76:77], v68, off offset:1152
	v_or_b32_e32 v77, v144, v143
	v_add_u32_e32 v86, s52, v77
	v_ashrrev_i32_e32 v87, 31, v86
	v_lshlrev_b64 v[68:69], 5, v[86:87]
	v_lshl_add_u64 v[82:83], s[48:49], 0, v[68:69]
	global_load_dwordx4 v[68:71], v[82:83], off offset:16
	global_load_dwordx4 v[72:75], v[82:83], off offset:48
	global_load_dwordx4 v[78:81], v[82:83], off
	s_nop 0
	global_load_dwordx4 v[82:85], v[82:83], off offset:32
	v_or_b32_e32 v86, 2, v86
	v_ashrrev_i32_e32 v87, 31, v86
	v_lshlrev_b64 v[86:87], 5, v[86:87]
	v_lshl_add_u64 v[98:99], s[48:49], 0, v[86:87]
	global_load_dwordx4 v[86:89], v[98:99], off offset:16
	global_load_dwordx4 v[90:93], v[98:99], off offset:48
	global_load_dwordx4 v[94:97], v[98:99], off
	s_nop 0
	global_load_dwordx4 v[98:101], v[98:99], off offset:32
	v_lshl_or_b32 v76, v142, 5, v139
	v_lshlrev_b32_e32 v104, 1, v77
	v_mul_u32_u24_e32 v76, 0x210, v76
	s_addc_u32 s13, s27, s13
	s_and_b32 s16, s52, 0xf00
	s_lshl_b32 s16, s16, 1
	s_add_u32 s40, s12, s16
	s_movk_i32 s16, 0x210
	s_addc_u32 s41, s13, 0
	s_waitcnt vmcnt(5)
	v_mov_b32_e32 v102, v78
	s_waitcnt vmcnt(4)
	v_mov_b32_e32 v103, v82
	v_mov_b32_e32 v82, v79
	v_pk_add_f32 v[78:79], v[102:103], v[82:83]
	v_mov_b32_e32 v82, v80
	v_mov_b32_e32 v83, v84
	v_mov_b32_e32 v84, v81
	v_pk_add_f32 v[80:81], v[82:83], v[84:85]
	s_nop 0
	v_pk_add_f32 v[78:79], v[78:79], v[80:81]
	v_mov_b32_e32 v80, v68
	v_mov_b32_e32 v81, v72
	v_mov_b32_e32 v72, v69
	v_pk_add_f32 v[68:69], v[80:81], v[72:73]
	v_mov_b32_e32 v72, v70
	v_mov_b32_e32 v73, v74
	v_mov_b32_e32 v74, v71
	v_pk_add_f32 v[68:69], v[78:79], v[68:69]
	v_pk_add_f32 v[70:71], v[72:73], v[74:75]
	s_waitcnt vmcnt(1)
	v_mov_b32_e32 v72, v96
	v_pk_add_f32 v[68:69], v[70:71], v[68:69]
	s_waitcnt vmcnt(0)
	v_mov_b32_e32 v73, v100
	v_pk_fma_f32 v[68:69], v[68:69], s[58:59], v[132:133] op_sel_hi:[1,0,0]
	v_mov_b32_e32 v100, v97
	v_mul_f32_e32 v70, 0x4b800000, v68
	v_cmp_gt_f32_e64 s[42:43], s33, v68
	v_cmp_gt_f32_e32 vcc, s33, v69
	v_pk_add_f32 v[72:73], v[72:73], v[100:101]
	v_cndmask_b32_e64 v68, v68, v70, s[42:43]
	v_mul_f32_e32 v70, 0x4b800000, v69
	v_cndmask_b32_e32 v69, v69, v70, vcc
	v_rsq_f32_e32 v68, v68
	v_rsq_f32_e32 v69, v69
	s_nop 0
	v_pk_mul_f32 v[70:71], v[68:69], s[54:55] op_sel_hi:[1,0]
	s_nop 0
	v_cndmask_b32_e32 v69, v69, v71, vcc
	v_cndmask_b32_e64 v68, v68, v70, s[42:43]
	v_mov_b32_e32 v70, v94
	v_mov_b32_e32 v71, v98
	v_mov_b32_e32 v98, v95
	v_pk_add_f32 v[70:71], v[70:71], v[98:99]
	v_pk_mul_f32 v[64:65], v[64:65], v[68:69]
	v_pk_add_f32 v[70:71], v[70:71], v[72:73]
	v_mov_b32_e32 v72, v86
	v_mov_b32_e32 v73, v90
	v_mov_b32_e32 v90, v87
	v_pk_add_f32 v[72:73], v[72:73], v[90:91]
	v_cvt_pk_bf16_f32 v64, v64, v65
	v_pk_add_f32 v[70:71], v[70:71], v[72:73]
	v_mov_b32_e32 v72, v88
	v_mov_b32_e32 v73, v92
	v_mov_b32_e32 v92, v89
	v_pk_add_f32 v[72:73], v[72:73], v[92:93]
	v_or_b32_e32 v94, 16, v77
	v_pk_add_f32 v[70:71], v[72:73], v[70:71]
	v_pk_mul_f32 v[60:61], v[60:61], v[68:69]
	v_pk_fma_f32 v[70:71], v[70:71], s[58:59], v[132:133] op_sel_hi:[1,0,0]
	v_add_u32_e32 v78, s52, v94
	v_mul_f32_e32 v65, 0x4b800000, v70
	v_cmp_gt_f32_e64 s[42:43], s33, v70
	v_cmp_gt_f32_e32 vcc, s33, v71
	v_cvt_pk_bf16_f32 v60, v60, v61
	v_cndmask_b32_e64 v65, v70, v65, s[42:43]
	v_rsq_f32_e32 v70, v65
	v_mul_f32_e32 v65, 0x4b800000, v71
	v_cndmask_b32_e32 v65, v71, v65, vcc
	v_rsq_f32_e32 v71, v65
	v_ashrrev_i32_e32 v79, 31, v78
	v_lshlrev_b32_e32 v96, 1, v94
	v_pk_mul_f32 v[72:73], v[70:71], s[54:55] op_sel_hi:[1,0]
	s_nop 0
	v_cndmask_b32_e32 v71, v71, v73, vcc
	v_cndmask_b32_e64 v70, v70, v72, s[42:43]
	v_pk_mul_f32 v[66:67], v[66:67], v[70:71]
	v_pk_mul_f32 v[62:63], v[62:63], v[70:71]
	v_cvt_pk_bf16_f32 v65, v66, v67
	v_add3_u32 v66, 0, v104, v76
	v_cvt_pk_bf16_f32 v61, v62, v63
	ds_write_b64 v66, v[60:61] offset:8448
	v_lshlrev_b64 v[60:61], 5, v[78:79]
	ds_write_b64 v66, v[64:65]
	v_lshl_add_u64 v[72:73], s[48:49], 0, v[60:61]
	global_load_dwordx4 v[60:63], v[72:73], off offset:16
	global_load_dwordx4 v[64:67], v[72:73], off offset:48
	global_load_dwordx4 v[68:71], v[72:73], off
	s_nop 0
	global_load_dwordx4 v[72:75], v[72:73], off offset:32
	v_or_b32_e32 v78, 2, v78
	v_ashrrev_i32_e32 v79, 31, v78
	v_lshlrev_b64 v[78:79], 5, v[78:79]
	v_lshl_add_u64 v[90:91], s[48:49], 0, v[78:79]
	global_load_dwordx4 v[78:81], v[90:91], off offset:16
	global_load_dwordx4 v[82:85], v[90:91], off offset:48
	global_load_dwordx4 v[86:89], v[90:91], off
	s_nop 0
	global_load_dwordx4 v[90:93], v[90:91], off offset:32
	s_waitcnt vmcnt(5)
; #define LAS __attribute__((address_space(3)))
; #define GAS __attribute__((address_space(1)))
; __device__ __forceinline__ unsigned cvtpk(float lo, float hi) { return __builtin_bit_cast(unsigned, __builtin_convertvector(f32x2_cv{lo, hi}, bf16x2_cv)); }
; template <int BJ_LO, int BJ_HI>
; __device__ __forceinline__ void vt_store_lds(const f32x4 (&acc)[2][2][4][2], int brow, int wr, int wc, int fr, int fq, const float* __restrict__ ssq, bf16_t* dst0) {
;     ...
;     for (int ai = 0; ai < 2; ++ai)
; #pragma unroll
;         for (int m = 0; m < 4; ++m) {
;             const int r0 = ai * 128 + wr * 64 + m * 16 + fq * 4;
;             float rs[4] = {1.f, 1.f, 1.f, 1.f};
;             if (ssq) {
; #pragma unroll
;                 for (int j = 0; j < 4; ++j) {
;                     const f32x4 a = *(const GAS f32x4*)(ssq + (size_t)(brow + r0 + j) * 8), c = *(const GAS f32x4*)(ssq + (size_t)(brow + r0 + j) * 8 + 4);
;                     rs[j] = rsqrtf(((a[0] + a[1]) + (a[2] + a[3]) + (c[0] + c[1]) + (c[2] + c[3])) * (1.f / 512.f) + RMS_EPS);
;                 }
;             }
; #pragma unroll
;             for (int bj = BJ_LO; bj < BJ_HI; ++bj)
; #pragma unroll
;                 for (int n = 0; n < 2; ++n) {
;                     const f32x4 a = acc[ai][bj][m][n];
;                     const int col = (bj - BJ_LO) * 128 + wc * 32 + n * 16 + fr;
;                     *(LAS u32x2*)(L + col * PITCH + r0 * 2) = u32x2{cvtpk(a[0] * rs[0], a[1] * rs[1]), cvtpk(a[2] * rs[2], a[3] * rs[3])};
;                 }
;         }
	v_mov_b32_e32 v94, v68
	s_waitcnt vmcnt(4)
	v_mov_b32_e32 v95, v72
	v_mov_b32_e32 v72, v69
	v_pk_add_f32 v[68:69], v[94:95], v[72:73]
	v_mov_b32_e32 v72, v70
	v_mov_b32_e32 v73, v74
	v_mov_b32_e32 v74, v71
	v_pk_add_f32 v[70:71], v[72:73], v[74:75]
	s_nop 0
	v_pk_add_f32 v[68:69], v[68:69], v[70:71]
	v_mov_b32_e32 v70, v60
	v_mov_b32_e32 v71, v64
	v_mov_b32_e32 v64, v61
	v_pk_add_f32 v[60:61], v[70:71], v[64:65]
	v_mov_b32_e32 v64, v62
	v_mov_b32_e32 v65, v66
	v_mov_b32_e32 v66, v63
	v_pk_add_f32 v[60:61], v[68:69], v[60:61]
	v_pk_add_f32 v[62:63], v[64:65], v[66:67]
	s_waitcnt vmcnt(1)
	v_mov_b32_e32 v64, v88
	v_pk_add_f32 v[60:61], v[62:63], v[60:61]
	s_waitcnt vmcnt(0)
	v_mov_b32_e32 v65, v92
	v_pk_fma_f32 v[60:61], v[60:61], s[58:59], v[132:133] op_sel_hi:[1,0,0]
	v_mov_b32_e32 v92, v89
	v_mul_f32_e32 v62, 0x4b800000, v60
	v_cmp_gt_f32_e64 s[42:43], s33, v60
	v_cmp_gt_f32_e32 vcc, s33, v61
	v_pk_add_f32 v[64:65], v[64:65], v[92:93]
	v_cndmask_b32_e64 v60, v60, v62, s[42:43]
	v_mul_f32_e32 v62, 0x4b800000, v61
	v_cndmask_b32_e32 v61, v61, v62, vcc
	v_rsq_f32_e32 v60, v60
	v_rsq_f32_e32 v61, v61
	s_nop 0
	v_pk_mul_f32 v[62:63], v[60:61], s[54:55] op_sel_hi:[1,0]
	s_nop 0
	v_cndmask_b32_e32 v61, v61, v63, vcc
	v_cndmask_b32_e64 v60, v60, v62, s[42:43]
	v_mov_b32_e32 v62, v86
	v_mov_b32_e32 v63, v90
	v_mov_b32_e32 v90, v87
	v_pk_add_f32 v[62:63], v[62:63], v[90:91]
	v_pk_mul_f32 v[56:57], v[56:57], v[60:61]
	v_pk_add_f32 v[62:63], v[62:63], v[64:65]
	v_mov_b32_e32 v64, v78
	v_mov_b32_e32 v65, v82
	v_mov_b32_e32 v82, v79
	v_pk_add_f32 v[64:65], v[64:65], v[82:83]
	v_cvt_pk_bf16_f32 v56, v56, v57
	v_pk_add_f32 v[62:63], v[62:63], v[64:65]
	v_mov_b32_e32 v64, v80
	v_mov_b32_e32 v65, v84
	v_mov_b32_e32 v84, v81
	v_pk_add_f32 v[64:65], v[64:65], v[84:85]
	v_or_b32_e32 v86, 32, v77
	v_pk_add_f32 v[62:63], v[64:65], v[62:63]
	v_pk_mul_f32 v[52:53], v[52:53], v[60:61]
	v_pk_fma_f32 v[62:63], v[62:63], s[58:59], v[132:133] op_sel_hi:[1,0,0]
	v_add_u32_e32 v68, s52, v86
	v_mul_f32_e32 v57, 0x4b800000, v62
	v_cmp_gt_f32_e64 s[42:43], s33, v62
	v_cmp_gt_f32_e32 vcc, s33, v63
	v_cvt_pk_bf16_f32 v52, v52, v53
	v_cndmask_b32_e64 v57, v62, v57, s[42:43]
	v_rsq_f32_e32 v62, v57
	v_mul_f32_e32 v57, 0x4b800000, v63
	v_cndmask_b32_e32 v57, v63, v57, vcc
	v_rsq_f32_e32 v63, v57
	v_ashrrev_i32_e32 v69, 31, v68
	v_lshlrev_b32_e32 v88, 1, v86
	v_pk_mul_f32 v[64:65], v[62:63], s[54:55] op_sel_hi:[1,0]
	s_nop 0
	v_cndmask_b32_e32 v63, v63, v65, vcc
	v_cndmask_b32_e64 v62, v62, v64, s[42:43]
	v_pk_mul_f32 v[58:59], v[58:59], v[62:63]
	v_pk_mul_f32 v[54:55], v[54:55], v[62:63]
	v_cvt_pk_bf16_f32 v57, v58, v59
	v_add3_u32 v58, 0, v96, v76
	v_cvt_pk_bf16_f32 v53, v54, v55
	ds_write_b64 v58, v[52:53] offset:8448
	v_lshlrev_b64 v[52:53], 5, v[68:69]
	ds_write_b64 v58, v[56:57]
	v_lshl_add_u64 v[64:65], s[48:49], 0, v[52:53]
	global_load_dwordx4 v[52:55], v[64:65], off offset:16
	global_load_dwordx4 v[56:59], v[64:65], off offset:48
	global_load_dwordx4 v[60:63], v[64:65], off
	s_nop 0
	global_load_dwordx4 v[64:67], v[64:65], off offset:32
	v_or_b32_e32 v68, 2, v68
	v_ashrrev_i32_e32 v69, 31, v68
	v_lshlrev_b64 v[68:69], 5, v[68:69]
	v_lshl_add_u64 v[82:83], s[48:49], 0, v[68:69]
	global_load_dwordx4 v[68:71], v[82:83], off offset:16
	global_load_dwordx4 v[72:75], v[82:83], off offset:48
	global_load_dwordx4 v[78:81], v[82:83], off
	s_nop 0
	global_load_dwordx4 v[82:85], v[82:83], off offset:32
	s_waitcnt vmcnt(5)
	v_mov_b32_e32 v86, v60
	s_waitcnt vmcnt(4)
	v_mov_b32_e32 v87, v64
	v_mov_b32_e32 v64, v61
	v_pk_add_f32 v[60:61], v[86:87], v[64:65]
	v_mov_b32_e32 v64, v62
	v_mov_b32_e32 v65, v66
	v_mov_b32_e32 v66, v63
	v_pk_add_f32 v[62:63], v[64:65], v[66:67]
	s_nop 0
	v_pk_add_f32 v[60:61], v[60:61], v[62:63]
	v_mov_b32_e32 v62, v52
	v_mov_b32_e32 v63, v56
	v_mov_b32_e32 v56, v53
	v_pk_add_f32 v[52:53], v[62:63], v[56:57]
	v_mov_b32_e32 v56, v54
	v_mov_b32_e32 v57, v58
	v_mov_b32_e32 v58, v55
	v_pk_add_f32 v[52:53], v[60:61], v[52:53]
	v_pk_add_f32 v[54:55], v[56:57], v[58:59]
	s_waitcnt vmcnt(1)
	v_mov_b32_e32 v56, v80
	v_pk_add_f32 v[52:53], v[54:55], v[52:53]
	s_waitcnt vmcnt(0)
	v_mov_b32_e32 v57, v84
	v_pk_fma_f32 v[52:53], v[52:53], s[58:59], v[132:133] op_sel_hi:[1,0,0]
	v_mov_b32_e32 v84, v81
	v_mul_f32_e32 v54, 0x4b800000, v52
	v_cmp_gt_f32_e64 s[42:43], s33, v52
	v_cmp_gt_f32_e32 vcc, s33, v53
	v_pk_add_f32 v[56:57], v[56:57], v[84:85]
	v_cndmask_b32_e64 v52, v52, v54, s[42:43]
	v_mul_f32_e32 v54, 0x4b800000, v53
	v_cndmask_b32_e32 v53, v53, v54, vcc
	v_rsq_f32_e32 v52, v52
	v_rsq_f32_e32 v53, v53
	s_nop 0
	v_pk_mul_f32 v[54:55], v[52:53], s[54:55] op_sel_hi:[1,0]
	s_nop 0
	v_cndmask_b32_e32 v53, v53, v55, vcc
	v_cndmask_b32_e64 v52, v52, v54, s[42:43]
	v_mov_b32_e32 v54, v78
	v_mov_b32_e32 v55, v82
	v_mov_b32_e32 v82, v79
	v_pk_add_f32 v[54:55], v[54:55], v[82:83]
	v_pk_mul_f32 v[48:49], v[48:49], v[52:53]
	v_pk_add_f32 v[54:55], v[54:55], v[56:57]
	v_mov_b32_e32 v56, v68
	v_mov_b32_e32 v57, v72
	v_mov_b32_e32 v72, v69
	v_pk_add_f32 v[56:57], v[56:57], v[72:73]
	v_cvt_pk_bf16_f32 v48, v48, v49
	v_pk_add_f32 v[54:55], v[54:55], v[56:57]
	v_mov_b32_e32 v56, v70
	v_mov_b32_e32 v57, v74
	v_mov_b32_e32 v74, v71
	v_pk_add_f32 v[56:57], v[56:57], v[74:75]
	v_or_b32_e32 v78, 48, v77
	v_pk_add_f32 v[54:55], v[56:57], v[54:55]
	v_pk_mul_f32 v[44:45], v[44:45], v[52:53]
	v_pk_fma_f32 v[54:55], v[54:55], s[58:59], v[132:133] op_sel_hi:[1,0,0]
	v_add_u32_e32 v60, s52, v78
	v_mul_f32_e32 v49, 0x4b800000, v54
	v_cmp_gt_f32_e64 s[42:43], s33, v54
	v_cmp_gt_f32_e32 vcc, s33, v55
	v_cvt_pk_bf16_f32 v44, v44, v45
	v_cndmask_b32_e64 v49, v54, v49, s[42:43]
	v_rsq_f32_e32 v54, v49
	v_mul_f32_e32 v49, 0x4b800000, v55
	v_cndmask_b32_e32 v49, v55, v49, vcc
	v_rsq_f32_e32 v55, v49
	v_ashrrev_i32_e32 v61, 31, v60
	v_lshlrev_b32_e32 v80, 1, v78
	v_pk_mul_f32 v[56:57], v[54:55], s[54:55] op_sel_hi:[1,0]
	s_nop 0
	v_cndmask_b32_e32 v55, v55, v57, vcc
	v_cndmask_b32_e64 v54, v54, v56, s[42:43]
	v_pk_mul_f32 v[50:51], v[50:51], v[54:55]
	v_pk_mul_f32 v[46:47], v[46:47], v[54:55]
	v_cvt_pk_bf16_f32 v49, v50, v51
	v_add3_u32 v50, 0, v88, v76
	v_cvt_pk_bf16_f32 v45, v46, v47
	ds_write_b64 v50, v[44:45] offset:8448
	v_lshlrev_b64 v[44:45], 5, v[60:61]
	ds_write_b64 v50, v[48:49]
	v_lshl_add_u64 v[56:57], s[48:49], 0, v[44:45]
	global_load_dwordx4 v[44:47], v[56:57], off offset:16
	global_load_dwordx4 v[48:51], v[56:57], off offset:48
	global_load_dwordx4 v[52:55], v[56:57], off
	s_nop 0
	global_load_dwordx4 v[56:59], v[56:57], off offset:32
	v_or_b32_e32 v60, 2, v60
	v_ashrrev_i32_e32 v61, 31, v60
	v_lshlrev_b64 v[60:61], 5, v[60:61]
	v_lshl_add_u64 v[72:73], s[48:49], 0, v[60:61]
	global_load_dwordx4 v[60:63], v[72:73], off offset:16
	global_load_dwordx4 v[64:67], v[72:73], off offset:48
	global_load_dwordx4 v[68:71], v[72:73], off
	s_nop 0
	global_load_dwordx4 v[72:75], v[72:73], off offset:32
	s_waitcnt vmcnt(5)
; #define LAS __attribute__((address_space(3)))
; #define GAS __attribute__((address_space(1)))
; __device__ __forceinline__ unsigned cvtpk(float lo, float hi) { return __builtin_bit_cast(unsigned, __builtin_convertvector(f32x2_cv{lo, hi}, bf16x2_cv)); }
; template <int BJ_LO, int BJ_HI>
; __device__ __forceinline__ void vt_store_lds(const f32x4 (&acc)[2][2][4][2], int brow, int wr, int wc, int fr, int fq, const float* __restrict__ ssq, bf16_t* dst0) {
;     ...
;     for (int ai = 0; ai < 2; ++ai)
; #pragma unroll
;         for (int m = 0; m < 4; ++m) {
;             const int r0 = ai * 128 + wr * 64 + m * 16 + fq * 4;
;             float rs[4] = {1.f, 1.f, 1.f, 1.f};
;             if (ssq) {
; #pragma unroll
;                 for (int j = 0; j < 4; ++j) {
;                     const f32x4 a = *(const GAS f32x4*)(ssq + (size_t)(brow + r0 + j) * 8), c = *(const GAS f32x4*)(ssq + (size_t)(brow + r0 + j) * 8 + 4);
;                     rs[j] = rsqrtf(((a[0] + a[1]) + (a[2] + a[3]) + (c[0] + c[1]) + (c[2] + c[3])) * (1.f / 512.f) + RMS_EPS);
;                 }
;             }
; #pragma unroll
;             for (int bj = BJ_LO; bj < BJ_HI; ++bj)
; #pragma unroll
;                 for (int n = 0; n < 2; ++n) {
;                     const f32x4 a = acc[ai][bj][m][n];
;                     const int col = (bj - BJ_LO) * 128 + wc * 32 + n * 16 + fr;
;                     *(LAS u32x2*)(L + col * PITCH + r0 * 2) = u32x2{cvtpk(a[0] * rs[0], a[1] * rs[1]), cvtpk(a[2] * rs[2], a[3] * rs[3])};
;                 }
;         }
	v_mov_b32_e32 v78, v52
	s_waitcnt vmcnt(4)
	v_mov_b32_e32 v79, v56
	v_mov_b32_e32 v56, v53
	v_pk_add_f32 v[52:53], v[78:79], v[56:57]
	v_mov_b32_e32 v56, v54
	v_mov_b32_e32 v57, v58
	v_mov_b32_e32 v58, v55
	v_pk_add_f32 v[54:55], v[56:57], v[58:59]
	s_nop 0
	v_pk_add_f32 v[52:53], v[52:53], v[54:55]
	v_mov_b32_e32 v54, v44
	v_mov_b32_e32 v55, v48
	v_mov_b32_e32 v48, v45
	v_pk_add_f32 v[44:45], v[54:55], v[48:49]
	v_mov_b32_e32 v48, v46
	v_mov_b32_e32 v49, v50
	v_mov_b32_e32 v50, v47
	v_pk_add_f32 v[44:45], v[52:53], v[44:45]
	v_pk_add_f32 v[46:47], v[48:49], v[50:51]
	s_waitcnt vmcnt(1)
	v_mov_b32_e32 v48, v70
	v_pk_add_f32 v[44:45], v[46:47], v[44:45]
	s_waitcnt vmcnt(0)
	v_mov_b32_e32 v49, v74
	v_pk_fma_f32 v[44:45], v[44:45], s[58:59], v[132:133] op_sel_hi:[1,0,0]
	v_mov_b32_e32 v74, v71
	v_mul_f32_e32 v46, 0x4b800000, v44
	v_cmp_gt_f32_e64 s[42:43], s33, v44
	v_cmp_gt_f32_e32 vcc, s33, v45
	v_pk_add_f32 v[48:49], v[48:49], v[74:75]
	v_cndmask_b32_e64 v44, v44, v46, s[42:43]
	v_mul_f32_e32 v46, 0x4b800000, v45
	v_cndmask_b32_e32 v45, v45, v46, vcc
	v_rsq_f32_e32 v44, v44
	v_rsq_f32_e32 v45, v45
	s_nop 0
	v_pk_mul_f32 v[46:47], v[44:45], s[54:55] op_sel_hi:[1,0]
	s_nop 0
	v_cndmask_b32_e32 v45, v45, v47, vcc
	v_cndmask_b32_e64 v44, v44, v46, s[42:43]
	v_mov_b32_e32 v46, v68
	v_mov_b32_e32 v47, v72
	v_mov_b32_e32 v72, v69
	v_pk_add_f32 v[46:47], v[46:47], v[72:73]
	v_pk_mul_f32 v[40:41], v[40:41], v[44:45]
	v_pk_add_f32 v[46:47], v[46:47], v[48:49]
	v_mov_b32_e32 v48, v60
	v_mov_b32_e32 v49, v64
	v_mov_b32_e32 v64, v61
	v_pk_add_f32 v[48:49], v[48:49], v[64:65]
	v_cvt_pk_bf16_f32 v40, v40, v41
	v_pk_add_f32 v[46:47], v[46:47], v[48:49]
	v_mov_b32_e32 v48, v62
	v_mov_b32_e32 v49, v66
	v_mov_b32_e32 v66, v63
	v_pk_add_f32 v[48:49], v[48:49], v[66:67]
	v_add_u32_e32 v68, 0x80, v77
	v_pk_add_f32 v[46:47], v[48:49], v[46:47]
	v_pk_mul_f32 v[36:37], v[36:37], v[44:45]
	v_pk_fma_f32 v[46:47], v[46:47], s[58:59], v[132:133] op_sel_hi:[1,0,0]
	v_add_u32_e32 v52, s52, v68
	v_mul_f32_e32 v41, 0x4b800000, v46
	v_cmp_gt_f32_e64 s[42:43], s33, v46
	v_cmp_gt_f32_e32 vcc, s33, v47
	v_cvt_pk_bf16_f32 v36, v36, v37
	v_cndmask_b32_e64 v41, v46, v41, s[42:43]
	v_rsq_f32_e32 v46, v41
	v_mul_f32_e32 v41, 0x4b800000, v47
	v_cndmask_b32_e32 v41, v47, v41, vcc
	v_rsq_f32_e32 v47, v41
	v_ashrrev_i32_e32 v53, 31, v52
	v_lshlrev_b32_e32 v70, 1, v68
	v_pk_mul_f32 v[48:49], v[46:47], s[54:55] op_sel_hi:[1,0]
	s_nop 0
	v_cndmask_b32_e32 v47, v47, v49, vcc
	v_cndmask_b32_e64 v46, v46, v48, s[42:43]
	v_pk_mul_f32 v[42:43], v[42:43], v[46:47]
	v_pk_mul_f32 v[38:39], v[38:39], v[46:47]
	v_cvt_pk_bf16_f32 v41, v42, v43
	v_add3_u32 v42, 0, v80, v76
	v_cvt_pk_bf16_f32 v37, v38, v39
	ds_write_b64 v42, v[36:37] offset:8448
	v_lshlrev_b64 v[36:37], 5, v[52:53]
	ds_write_b64 v42, v[40:41]
	v_lshl_add_u64 v[48:49], s[48:49], 0, v[36:37]
	global_load_dwordx4 v[36:39], v[48:49], off offset:16
	global_load_dwordx4 v[40:43], v[48:49], off offset:48
	global_load_dwordx4 v[44:47], v[48:49], off
	s_nop 0
	global_load_dwordx4 v[48:51], v[48:49], off offset:32
	v_or_b32_e32 v52, 2, v52
	v_ashrrev_i32_e32 v53, 31, v52
	v_lshlrev_b64 v[52:53], 5, v[52:53]
	v_lshl_add_u64 v[64:65], s[48:49], 0, v[52:53]
	global_load_dwordx4 v[52:55], v[64:65], off offset:16
	global_load_dwordx4 v[56:59], v[64:65], off offset:48
	global_load_dwordx4 v[60:63], v[64:65], off
	s_nop 0
	global_load_dwordx4 v[64:67], v[64:65], off offset:32
	s_waitcnt vmcnt(5)
	v_mov_b32_e32 v68, v44
	s_waitcnt vmcnt(4)
	v_mov_b32_e32 v69, v48
	v_mov_b32_e32 v48, v45
	v_pk_add_f32 v[44:45], v[68:69], v[48:49]
	v_mov_b32_e32 v48, v46
	v_mov_b32_e32 v49, v50
	v_mov_b32_e32 v50, v47
	v_pk_add_f32 v[46:47], v[48:49], v[50:51]
	s_nop 0
	v_pk_add_f32 v[44:45], v[44:45], v[46:47]
	v_mov_b32_e32 v46, v36
	v_mov_b32_e32 v47, v40
	v_mov_b32_e32 v40, v37
	v_pk_add_f32 v[36:37], v[46:47], v[40:41]
	v_mov_b32_e32 v40, v38
	v_mov_b32_e32 v41, v42
	v_mov_b32_e32 v42, v39
	v_pk_add_f32 v[36:37], v[44:45], v[36:37]
	v_pk_add_f32 v[38:39], v[40:41], v[42:43]
	s_waitcnt vmcnt(1)
	v_mov_b32_e32 v40, v62
	v_pk_add_f32 v[36:37], v[38:39], v[36:37]
	s_waitcnt vmcnt(0)
	v_mov_b32_e32 v41, v66
	v_pk_fma_f32 v[36:37], v[36:37], s[58:59], v[132:133] op_sel_hi:[1,0,0]
	v_mov_b32_e32 v66, v63
	v_mul_f32_e32 v38, 0x4b800000, v36
	v_cmp_gt_f32_e64 s[42:43], s33, v36
	v_cmp_gt_f32_e32 vcc, s33, v37
	v_pk_add_f32 v[40:41], v[40:41], v[66:67]
	v_cndmask_b32_e64 v36, v36, v38, s[42:43]
	v_mul_f32_e32 v38, 0x4b800000, v37
	v_cndmask_b32_e32 v37, v37, v38, vcc
	v_rsq_f32_e32 v36, v36
	v_rsq_f32_e32 v37, v37
	s_nop 0
	v_pk_mul_f32 v[38:39], v[36:37], s[54:55] op_sel_hi:[1,0]
	s_nop 0
	v_cndmask_b32_e32 v37, v37, v39, vcc
	v_cndmask_b32_e64 v36, v36, v38, s[42:43]
	v_mov_b32_e32 v38, v60
	v_mov_b32_e32 v39, v64
	v_mov_b32_e32 v64, v61
	v_pk_add_f32 v[38:39], v[38:39], v[64:65]
	v_pk_mul_f32 v[32:33], v[32:33], v[36:37]
	v_pk_add_f32 v[38:39], v[38:39], v[40:41]
	v_mov_b32_e32 v40, v52
	v_mov_b32_e32 v41, v56
	v_mov_b32_e32 v56, v53
	v_pk_add_f32 v[40:41], v[40:41], v[56:57]
	v_cvt_pk_bf16_f32 v32, v32, v33
	v_pk_add_f32 v[38:39], v[38:39], v[40:41]
	v_mov_b32_e32 v40, v54
	v_mov_b32_e32 v41, v58
	v_mov_b32_e32 v58, v55
	v_pk_add_f32 v[40:41], v[40:41], v[58:59]
	v_add_u32_e32 v60, 0x90, v77
	v_pk_add_f32 v[38:39], v[40:41], v[38:39]
	v_pk_mul_f32 v[28:29], v[28:29], v[36:37]
	v_pk_fma_f32 v[38:39], v[38:39], s[58:59], v[132:133] op_sel_hi:[1,0,0]
	v_add_u32_e32 v44, s52, v60
	v_mul_f32_e32 v33, 0x4b800000, v38
	v_cmp_gt_f32_e64 s[42:43], s33, v38
	v_cmp_gt_f32_e32 vcc, s33, v39
	v_cvt_pk_bf16_f32 v28, v28, v29
	v_cndmask_b32_e64 v33, v38, v33, s[42:43]
	v_rsq_f32_e32 v38, v33
	v_mul_f32_e32 v33, 0x4b800000, v39
	v_cndmask_b32_e32 v33, v39, v33, vcc
	v_rsq_f32_e32 v39, v33
	v_ashrrev_i32_e32 v45, 31, v44
	v_lshlrev_b32_e32 v62, 1, v60
	v_pk_mul_f32 v[40:41], v[38:39], s[54:55] op_sel_hi:[1,0]
	s_nop 0
	v_cndmask_b32_e32 v39, v39, v41, vcc
	v_cndmask_b32_e64 v38, v38, v40, s[42:43]
	v_pk_mul_f32 v[34:35], v[34:35], v[38:39]
	v_pk_mul_f32 v[30:31], v[30:31], v[38:39]
	v_cvt_pk_bf16_f32 v33, v34, v35
	v_add3_u32 v34, 0, v70, v76
	v_cvt_pk_bf16_f32 v29, v30, v31
	ds_write_b64 v34, v[28:29] offset:8448
	v_lshlrev_b64 v[28:29], 5, v[44:45]
	ds_write_b64 v34, v[32:33]
	v_lshl_add_u64 v[40:41], s[48:49], 0, v[28:29]
	global_load_dwordx4 v[28:31], v[40:41], off offset:16
	global_load_dwordx4 v[32:35], v[40:41], off offset:48
	global_load_dwordx4 v[36:39], v[40:41], off
	s_nop 0
	global_load_dwordx4 v[40:43], v[40:41], off offset:32
	v_or_b32_e32 v44, 2, v44
	v_ashrrev_i32_e32 v45, 31, v44
	v_lshlrev_b64 v[44:45], 5, v[44:45]
	v_lshl_add_u64 v[56:57], s[48:49], 0, v[44:45]
	global_load_dwordx4 v[44:47], v[56:57], off offset:16
	global_load_dwordx4 v[48:51], v[56:57], off offset:48
	global_load_dwordx4 v[52:55], v[56:57], off
	s_nop 0
	global_load_dwordx4 v[56:59], v[56:57], off offset:32
	s_waitcnt vmcnt(5)
; #define LAS __attribute__((address_space(3)))
; #define GAS __attribute__((address_space(1)))
; __device__ __forceinline__ unsigned cvtpk(float lo, float hi) { return __builtin_bit_cast(unsigned, __builtin_convertvector(f32x2_cv{lo, hi}, bf16x2_cv)); }
; template <int BJ_LO, int BJ_HI>
; __device__ __forceinline__ void vt_store_lds(const f32x4 (&acc)[2][2][4][2], int brow, int wr, int wc, int fr, int fq, const float* __restrict__ ssq, bf16_t* dst0) {
;     ...
;     for (int ai = 0; ai < 2; ++ai)
; #pragma unroll
;         for (int m = 0; m < 4; ++m) {
;             const int r0 = ai * 128 + wr * 64 + m * 16 + fq * 4;
;             float rs[4] = {1.f, 1.f, 1.f, 1.f};
;             if (ssq) {
; #pragma unroll
;                 for (int j = 0; j < 4; ++j) {
;                     const f32x4 a = *(const GAS f32x4*)(ssq + (size_t)(brow + r0 + j) * 8), c = *(const GAS f32x4*)(ssq + (size_t)(brow + r0 + j) * 8 + 4);
;                     rs[j] = rsqrtf(((a[0] + a[1]) + (a[2] + a[3]) + (c[0] + c[1]) + (c[2] + c[3])) * (1.f / 512.f) + RMS_EPS);
;                 }
;             }
; #pragma unroll
;             for (int bj = BJ_LO; bj < BJ_HI; ++bj)
; #pragma unroll
;                 for (int n = 0; n < 2; ++n) {
;                     const f32x4 a = acc[ai][bj][m][n];
;                     const int col = (bj - BJ_LO) * 128 + wc * 32 + n * 16 + fr;
;                     *(LAS u32x2*)(L + col * PITCH + r0 * 2) = u32x2{cvtpk(a[0] * rs[0], a[1] * rs[1]), cvtpk(a[2] * rs[2], a[3] * rs[3])};
;                 }
;         }
	v_mov_b32_e32 v60, v36
	s_waitcnt vmcnt(4)
	v_mov_b32_e32 v61, v40
	v_mov_b32_e32 v40, v37
	v_pk_add_f32 v[36:37], v[60:61], v[40:41]
	v_mov_b32_e32 v40, v38
	v_mov_b32_e32 v41, v42
	v_mov_b32_e32 v42, v39
	v_pk_add_f32 v[38:39], v[40:41], v[42:43]
	s_nop 0
	v_pk_add_f32 v[36:37], v[36:37], v[38:39]
	v_mov_b32_e32 v38, v28
	v_mov_b32_e32 v39, v32
	v_mov_b32_e32 v32, v29
	v_pk_add_f32 v[28:29], v[38:39], v[32:33]
	v_mov_b32_e32 v32, v30
	v_mov_b32_e32 v33, v34
	v_mov_b32_e32 v34, v31
	v_pk_add_f32 v[28:29], v[36:37], v[28:29]
	v_pk_add_f32 v[30:31], v[32:33], v[34:35]
	s_waitcnt vmcnt(1)
	v_mov_b32_e32 v32, v54
	v_pk_add_f32 v[28:29], v[30:31], v[28:29]
	s_waitcnt vmcnt(0)
	v_mov_b32_e32 v33, v58
	v_pk_fma_f32 v[28:29], v[28:29], s[58:59], v[132:133] op_sel_hi:[1,0,0]
	v_mov_b32_e32 v58, v55
	v_mul_f32_e32 v30, 0x4b800000, v28
	v_cmp_gt_f32_e64 s[42:43], s33, v28
	v_cmp_gt_f32_e32 vcc, s33, v29
	v_pk_add_f32 v[32:33], v[32:33], v[58:59]
	v_cndmask_b32_e64 v28, v28, v30, s[42:43]
	v_mul_f32_e32 v30, 0x4b800000, v29
	v_cndmask_b32_e32 v29, v29, v30, vcc
	v_rsq_f32_e32 v28, v28
	v_rsq_f32_e32 v29, v29
	s_nop 0
	v_pk_mul_f32 v[30:31], v[28:29], s[54:55] op_sel_hi:[1,0]
	s_nop 0
	v_cndmask_b32_e32 v29, v29, v31, vcc
	v_cndmask_b32_e64 v28, v28, v30, s[42:43]
	v_mov_b32_e32 v30, v52
	v_mov_b32_e32 v31, v56
	v_mov_b32_e32 v56, v53
	v_pk_add_f32 v[30:31], v[30:31], v[56:57]
	v_pk_mul_f32 v[24:25], v[24:25], v[28:29]
	v_pk_add_f32 v[30:31], v[30:31], v[32:33]
	v_mov_b32_e32 v32, v44
	v_mov_b32_e32 v33, v48
	v_mov_b32_e32 v48, v45
	v_pk_add_f32 v[32:33], v[32:33], v[48:49]
	v_cvt_pk_bf16_f32 v24, v24, v25
	v_pk_add_f32 v[30:31], v[30:31], v[32:33]
	v_mov_b32_e32 v32, v46
	v_mov_b32_e32 v33, v50
	v_mov_b32_e32 v50, v47
	v_pk_add_f32 v[32:33], v[32:33], v[50:51]
	v_add_u32_e32 v52, 0xa0, v77
	v_pk_add_f32 v[30:31], v[32:33], v[30:31]
	v_pk_mul_f32 v[20:21], v[20:21], v[28:29]
	v_pk_fma_f32 v[30:31], v[30:31], s[58:59], v[132:133] op_sel_hi:[1,0,0]
	v_add_u32_e32 v36, s52, v52
	v_mul_f32_e32 v25, 0x4b800000, v30
	v_cmp_gt_f32_e64 s[42:43], s33, v30
	v_cmp_gt_f32_e32 vcc, s33, v31
	v_cvt_pk_bf16_f32 v20, v20, v21
	v_cndmask_b32_e64 v25, v30, v25, s[42:43]
	v_rsq_f32_e32 v30, v25
	v_mul_f32_e32 v25, 0x4b800000, v31
	v_cndmask_b32_e32 v25, v31, v25, vcc
	v_rsq_f32_e32 v31, v25
	v_ashrrev_i32_e32 v37, 31, v36
	v_lshlrev_b32_e32 v54, 1, v52
	v_pk_mul_f32 v[32:33], v[30:31], s[54:55] op_sel_hi:[1,0]
	s_nop 0
	v_cndmask_b32_e32 v31, v31, v33, vcc
	v_cndmask_b32_e64 v30, v30, v32, s[42:43]
	v_pk_mul_f32 v[26:27], v[26:27], v[30:31]
	v_pk_mul_f32 v[22:23], v[22:23], v[30:31]
	v_cvt_pk_bf16_f32 v25, v26, v27
	v_add3_u32 v26, 0, v62, v76
	v_cvt_pk_bf16_f32 v21, v22, v23
	ds_write_b64 v26, v[20:21] offset:8448
	v_lshlrev_b64 v[20:21], 5, v[36:37]
	ds_write_b64 v26, v[24:25]
	v_lshl_add_u64 v[32:33], s[48:49], 0, v[20:21]
	global_load_dwordx4 v[20:23], v[32:33], off offset:16
	global_load_dwordx4 v[24:27], v[32:33], off offset:48
	global_load_dwordx4 v[28:31], v[32:33], off
	s_nop 0
	global_load_dwordx4 v[32:35], v[32:33], off offset:32
	v_or_b32_e32 v36, 2, v36
	v_ashrrev_i32_e32 v37, 31, v36
	v_lshlrev_b64 v[36:37], 5, v[36:37]
	v_lshl_add_u64 v[48:49], s[48:49], 0, v[36:37]
	global_load_dwordx4 v[36:39], v[48:49], off offset:16
	global_load_dwordx4 v[40:43], v[48:49], off offset:48
	global_load_dwordx4 v[44:47], v[48:49], off
	s_nop 0
	global_load_dwordx4 v[48:51], v[48:49], off offset:32
	s_waitcnt vmcnt(5)
	v_mov_b32_e32 v52, v28
	s_waitcnt vmcnt(4)
	v_mov_b32_e32 v53, v32
	v_mov_b32_e32 v32, v29
	v_pk_add_f32 v[28:29], v[52:53], v[32:33]
	v_mov_b32_e32 v32, v30
	v_mov_b32_e32 v33, v34
	v_mov_b32_e32 v34, v31
	v_pk_add_f32 v[30:31], v[32:33], v[34:35]
	s_nop 0
	v_pk_add_f32 v[28:29], v[28:29], v[30:31]
	v_mov_b32_e32 v30, v20
	v_mov_b32_e32 v31, v24
	v_mov_b32_e32 v24, v21
	v_pk_add_f32 v[20:21], v[30:31], v[24:25]
	v_mov_b32_e32 v24, v22
	v_mov_b32_e32 v25, v26
	v_mov_b32_e32 v26, v23
	v_pk_add_f32 v[20:21], v[28:29], v[20:21]
	v_pk_add_f32 v[22:23], v[24:25], v[26:27]
	s_waitcnt vmcnt(1)
	v_mov_b32_e32 v24, v46
	v_pk_add_f32 v[20:21], v[22:23], v[20:21]
	s_waitcnt vmcnt(0)
	v_mov_b32_e32 v25, v50
	v_pk_fma_f32 v[20:21], v[20:21], s[58:59], v[132:133] op_sel_hi:[1,0,0]
	v_mov_b32_e32 v50, v47
	v_mul_f32_e32 v22, 0x4b800000, v20
	v_cmp_gt_f32_e64 s[42:43], s33, v20
	v_cmp_gt_f32_e32 vcc, s33, v21
	v_pk_add_f32 v[24:25], v[24:25], v[50:51]
	v_cndmask_b32_e64 v20, v20, v22, s[42:43]
	v_mul_f32_e32 v22, 0x4b800000, v21
	v_cndmask_b32_e32 v21, v21, v22, vcc
	v_rsq_f32_e32 v20, v20
	v_rsq_f32_e32 v21, v21
	s_nop 0
	v_pk_mul_f32 v[22:23], v[20:21], s[54:55] op_sel_hi:[1,0]
	s_nop 0
	v_cndmask_b32_e32 v21, v21, v23, vcc
	v_cndmask_b32_e64 v20, v20, v22, s[42:43]
	v_mov_b32_e32 v22, v44
	v_mov_b32_e32 v23, v48
	v_mov_b32_e32 v48, v45
	v_pk_add_f32 v[22:23], v[22:23], v[48:49]
	v_pk_mul_f32 v[16:17], v[16:17], v[20:21]
	v_pk_add_f32 v[22:23], v[22:23], v[24:25]
	v_mov_b32_e32 v24, v36
	v_mov_b32_e32 v25, v40
	v_mov_b32_e32 v40, v37
	v_pk_add_f32 v[24:25], v[24:25], v[40:41]
	v_cvt_pk_bf16_f32 v16, v16, v17
	v_pk_add_f32 v[22:23], v[22:23], v[24:25]
	v_mov_b32_e32 v24, v38
	v_mov_b32_e32 v25, v42
	v_mov_b32_e32 v42, v39
	v_pk_add_f32 v[24:25], v[24:25], v[42:43]
	v_add_u32_e32 v44, 0xb0, v77
	v_pk_add_f32 v[22:23], v[24:25], v[22:23]
	v_pk_mul_f32 v[12:13], v[12:13], v[20:21]
	v_pk_fma_f32 v[22:23], v[22:23], s[58:59], v[132:133] op_sel_hi:[1,0,0]
	v_add_u32_e32 v28, s52, v44
	v_mul_f32_e32 v17, 0x4b800000, v22
	v_cmp_gt_f32_e64 s[42:43], s33, v22
	v_cmp_gt_f32_e32 vcc, s33, v23
	v_cvt_pk_bf16_f32 v12, v12, v13
	v_cndmask_b32_e64 v17, v22, v17, s[42:43]
	v_rsq_f32_e32 v22, v17
	v_mul_f32_e32 v17, 0x4b800000, v23
	v_cndmask_b32_e32 v17, v23, v17, vcc
	v_rsq_f32_e32 v23, v17
	v_ashrrev_i32_e32 v29, 31, v28
	v_lshlrev_b32_e32 v46, 1, v44
	v_pk_mul_f32 v[24:25], v[22:23], s[54:55] op_sel_hi:[1,0]
	s_nop 0
	v_cndmask_b32_e32 v23, v23, v25, vcc
	v_cndmask_b32_e64 v22, v22, v24, s[42:43]
	v_pk_mul_f32 v[18:19], v[18:19], v[22:23]
	v_pk_mul_f32 v[14:15], v[14:15], v[22:23]
	v_cvt_pk_bf16_f32 v17, v18, v19
	v_add3_u32 v18, 0, v54, v76
	v_cvt_pk_bf16_f32 v13, v14, v15
	ds_write_b64 v18, v[12:13] offset:8448
	v_lshlrev_b64 v[12:13], 5, v[28:29]
	ds_write_b64 v18, v[16:17]
	v_lshl_add_u64 v[24:25], s[48:49], 0, v[12:13]
	global_load_dwordx4 v[16:19], v[24:25], off offset:16
	global_load_dwordx4 v[12:15], v[24:25], off offset:48
	global_load_dwordx4 v[20:23], v[24:25], off
	s_nop 0
	global_load_dwordx4 v[24:27], v[24:25], off offset:32
	v_or_b32_e32 v28, 2, v28
	v_ashrrev_i32_e32 v29, 31, v28
	v_lshlrev_b64 v[28:29], 5, v[28:29]
	v_lshl_add_u64 v[40:41], s[48:49], 0, v[28:29]
	global_load_dwordx4 v[32:35], v[40:41], off offset:16
	global_load_dwordx4 v[28:31], v[40:41], off offset:48
	global_load_dwordx4 v[36:39], v[40:41], off
	s_nop 0
	global_load_dwordx4 v[40:43], v[40:41], off offset:32
	s_waitcnt vmcnt(5)
; #define LAS __attribute__((address_space(3)))
; #define GAS __attribute__((address_space(1)))
; __device__ __forceinline__ unsigned cvtpk(float lo, float hi) { return __builtin_bit_cast(unsigned, __builtin_convertvector(f32x2_cv{lo, hi}, bf16x2_cv)); }
; template <int BJ_LO, int BJ_HI>
; __device__ __forceinline__ void vt_store_lds(const f32x4 (&acc)[2][2][4][2], int brow, int wr, int wc, int fr, int fq, const float* __restrict__ ssq, bf16_t* dst0) {
;     ...
;     for (int ai = 0; ai < 2; ++ai)
; #pragma unroll
;         for (int m = 0; m < 4; ++m) {
;             const int r0 = ai * 128 + wr * 64 + m * 16 + fq * 4;
;             float rs[4] = {1.f, 1.f, 1.f, 1.f};
;             if (ssq) {
; #pragma unroll
;                 for (int j = 0; j < 4; ++j) {
;                     const f32x4 a = *(const GAS f32x4*)(ssq + (size_t)(brow + r0 + j) * 8), c = *(const GAS f32x4*)(ssq + (size_t)(brow + r0 + j) * 8 + 4);
;                     rs[j] = rsqrtf(((a[0] + a[1]) + (a[2] + a[3]) + (c[0] + c[1]) + (c[2] + c[3])) * (1.f / 512.f) + RMS_EPS);
;                 }
;             }
; #pragma unroll
;             for (int bj = BJ_LO; bj < BJ_HI; ++bj)
; #pragma unroll
;                 for (int n = 0; n < 2; ++n) {
;                     const f32x4 a = acc[ai][bj][m][n];
;                     const int col = (bj - BJ_LO) * 128 + wc * 32 + n * 16 + fr;
;                     *(LAS u32x2*)(L + col * PITCH + r0 * 2) = u32x2{cvtpk(a[0] * rs[0], a[1] * rs[1]), cvtpk(a[2] * rs[2], a[3] * rs[3])};
;                 }
;         }
;     __syncthreads();
;     const int tid = (wr * 4 + wc) * 64 + fq * 16 + fr;
;     constexpr int NCH = (BJ_HI - BJ_LO) * 128 * 32;
; #pragma unroll
;     for (int ch = 0; ch < NCH; ch += NTHR) {
;         const int col = (ch + tid) >> 5, tc = (ch + tid) & 31;
;         const u32x4 t = *(const LAS u32x4*)(L + col * PITCH + tc * 16);
;         *(GAS u32x4*)((GAS bf16_t*)dst0 + (size_t)col * S + tc * 8) = t;
;     }
;     __syncthreads();
	v_mov_b32_e32 v44, v20
	s_waitcnt vmcnt(4)
	v_mov_b32_e32 v45, v24
	v_mov_b32_e32 v24, v21
	v_pk_add_f32 v[20:21], v[44:45], v[24:25]
	v_mov_b32_e32 v24, v22
	v_mov_b32_e32 v25, v26
	v_mov_b32_e32 v26, v23
	v_pk_add_f32 v[22:23], v[24:25], v[26:27]
	s_nop 0
	v_pk_add_f32 v[20:21], v[20:21], v[22:23]
	v_mov_b32_e32 v22, v16
	v_mov_b32_e32 v23, v12
	v_mov_b32_e32 v12, v17
	v_pk_add_f32 v[12:13], v[22:23], v[12:13]
	v_mov_b32_e32 v16, v18
	v_mov_b32_e32 v17, v14
	v_mov_b32_e32 v14, v19
	v_pk_add_f32 v[12:13], v[20:21], v[12:13]
	v_pk_add_f32 v[14:15], v[16:17], v[14:15]
	s_waitcnt vmcnt(1)
	v_mov_b32_e32 v16, v38
	v_pk_add_f32 v[12:13], v[14:15], v[12:13]
	s_waitcnt vmcnt(0)
	v_mov_b32_e32 v17, v42
	v_pk_fma_f32 v[12:13], v[12:13], s[58:59], v[132:133] op_sel_hi:[1,0,0]
	v_mov_b32_e32 v42, v39
	v_mul_f32_e32 v14, 0x4b800000, v12
	v_cmp_gt_f32_e64 s[42:43], s33, v12
	v_cmp_gt_f32_e32 vcc, s33, v13
	v_pk_add_f32 v[16:17], v[16:17], v[42:43]
	v_cndmask_b32_e64 v12, v12, v14, s[42:43]
	v_mul_f32_e32 v14, 0x4b800000, v13
	v_cndmask_b32_e32 v13, v13, v14, vcc
	v_rsq_f32_e32 v12, v12
	v_rsq_f32_e32 v13, v13
	s_nop 0
	v_pk_mul_f32 v[14:15], v[12:13], s[54:55] op_sel_hi:[1,0]
	s_nop 0
	v_cndmask_b32_e32 v13, v13, v15, vcc
	v_cndmask_b32_e64 v12, v12, v14, s[42:43]
	v_mov_b32_e32 v14, v36
	v_mov_b32_e32 v15, v40
	v_mov_b32_e32 v40, v37
	v_pk_add_f32 v[14:15], v[14:15], v[40:41]
	v_pk_mul_f32 v[8:9], v[8:9], v[12:13]
	v_pk_add_f32 v[14:15], v[14:15], v[16:17]
	v_mov_b32_e32 v16, v32
	v_mov_b32_e32 v17, v28
	v_mov_b32_e32 v28, v33
	v_pk_add_f32 v[16:17], v[16:17], v[28:29]
	v_cvt_pk_bf16_f32 v8, v8, v9
	v_pk_add_f32 v[14:15], v[14:15], v[16:17]
	v_mov_b32_e32 v16, v34
	v_mov_b32_e32 v17, v30
	v_mov_b32_e32 v30, v35
	v_pk_add_f32 v[16:17], v[16:17], v[30:31]
	v_pk_mul_f32 v[4:5], v[4:5], v[12:13]
	v_pk_add_f32 v[14:15], v[16:17], v[14:15]
	v_cvt_pk_bf16_f32 v4, v4, v5
	v_pk_fma_f32 v[14:15], v[14:15], s[58:59], v[132:133] op_sel_hi:[1,0,0]
	v_ashrrev_i32_e32 v12, 5, v1
	v_mul_f32_e32 v9, 0x4b800000, v14
	v_cmp_gt_f32_e64 s[42:43], s33, v14
	v_cmp_gt_f32_e32 vcc, s33, v15
	v_ashrrev_i32_e32 v13, 31, v12
	v_cndmask_b32_e64 v9, v14, v9, s[42:43]
	v_rsq_f32_e32 v14, v9
	v_mul_f32_e32 v9, 0x4b800000, v15
	v_cndmask_b32_e32 v9, v15, v9, vcc
	v_rsq_f32_e32 v15, v9
	s_nop 0
	v_pk_mul_f32 v[16:17], v[14:15], s[54:55] op_sel_hi:[1,0]
	s_nop 0
	v_cndmask_b32_e32 v15, v15, v17, vcc
	v_cndmask_b32_e64 v14, v14, v16, s[42:43]
	v_pk_mul_f32 v[10:11], v[10:11], v[14:15]
	v_pk_mul_f32 v[6:7], v[6:7], v[14:15]
	v_cvt_pk_bf16_f32 v9, v10, v11
	v_add3_u32 v10, 0, v46, v76
	ds_write_b64 v10, v[8:9]
	v_cvt_pk_bf16_f32 v5, v6, v7
	v_add_u32_e32 v8, 0, v2
	ds_write_b64 v10, v[4:5] offset:8448
	v_mad_u64_u32 v[4:5], s[12:13], v12, s16, v[8:9]
	s_waitcnt lgkmcnt(0)
	s_barrier
	ds_read_b128 v[4:7], v4
	v_lshl_add_u64 v[10:11], s[40:41], 0, v[2:3]
	v_lshlrev_b64 v[12:13], 13, v[12:13]
	v_lshl_add_u64 v[12:13], v[10:11], 0, v[12:13]
	v_add_u32_e32 v2, 0x200, v1
	s_waitcnt lgkmcnt(0)
	global_store_dwordx4 v[12:13], v[4:7], off
	v_ashrrev_i32_e32 v12, 5, v2
	v_ashrrev_i32_e32 v13, 31, v12
	v_mad_u64_u32 v[4:5], s[12:13], v12, s16, v[8:9]
	ds_read_b128 v[4:7], v4
	v_lshlrev_b64 v[12:13], 13, v[12:13]
	v_lshl_add_u64 v[12:13], v[10:11], 0, v[12:13]
	v_add_u32_e32 v2, 0x400, v1
	s_waitcnt lgkmcnt(0)
	global_store_dwordx4 v[12:13], v[4:7], off
	v_ashrrev_i32_e32 v12, 5, v2
	s_nop 0
	v_mad_u64_u32 v[4:5], s[12:13], v12, s16, v[8:9]
	ds_read_b128 v[4:7], v4
	v_ashrrev_i32_e32 v13, 31, v12
	v_lshlrev_b64 v[12:13], 13, v[12:13]
	v_lshl_add_u64 v[12:13], v[10:11], 0, v[12:13]
	v_add_u32_e32 v2, 0x600, v1
	s_waitcnt lgkmcnt(0)
	global_store_dwordx4 v[12:13], v[4:7], off
	v_ashrrev_i32_e32 v12, 5, v2
	v_ashrrev_i32_e32 v13, 31, v12
	v_mad_u64_u32 v[4:5], s[12:13], v12, s16, v[8:9]
	ds_read_b128 v[4:7], v4
	v_lshlrev_b64 v[12:13], 13, v[12:13]
	v_lshl_add_u64 v[12:13], v[10:11], 0, v[12:13]
	v_add_u32_e32 v2, 0x800, v1
	s_waitcnt lgkmcnt(0)
	global_store_dwordx4 v[12:13], v[4:7], off
	v_ashrrev_i32_e32 v12, 5, v2
	s_nop 0
	v_mad_u64_u32 v[4:5], s[12:13], v12, s16, v[8:9]
	ds_read_b128 v[4:7], v4
	v_ashrrev_i32_e32 v13, 31, v12
	v_lshlrev_b64 v[12:13], 13, v[12:13]
	v_lshl_add_u64 v[12:13], v[10:11], 0, v[12:13]
	v_add_u32_e32 v2, 0xa00, v1
	s_waitcnt lgkmcnt(0)
	global_store_dwordx4 v[12:13], v[4:7], off
	v_ashrrev_i32_e32 v12, 5, v2
	v_ashrrev_i32_e32 v13, 31, v12
	v_mad_u64_u32 v[4:5], s[12:13], v12, s16, v[8:9]
	ds_read_b128 v[4:7], v4
	v_lshlrev_b64 v[12:13], 13, v[12:13]
	v_lshl_add_u64 v[12:13], v[10:11], 0, v[12:13]
	v_add_u32_e32 v2, 0xc00, v1
	v_add_u32_e32 v1, 0xe00, v1
	s_waitcnt lgkmcnt(0)
	global_store_dwordx4 v[12:13], v[4:7], off
	v_ashrrev_i32_e32 v12, 5, v2
	v_ashrrev_i32_e32 v13, 31, v12
	v_mad_u64_u32 v[4:5], s[12:13], v12, s16, v[8:9]
	ds_read_b128 v[4:7], v4
	v_lshlrev_b64 v[12:13], 13, v[12:13]
	v_lshl_add_u64 v[12:13], v[10:11], 0, v[12:13]
	s_waitcnt lgkmcnt(0)
	global_store_dwordx4 v[12:13], v[4:7], off
	v_ashrrev_i32_e32 v12, 5, v1
	s_nop 0
	v_mad_u64_u32 v[4:5], s[12:13], v12, s16, v[8:9]
	ds_read_b128 v[4:7], v4
	v_ashrrev_i32_e32 v13, 31, v12
	v_lshlrev_b64 v[8:9], 13, v[12:13]
	s_add_i32 s12, s28, 0x100
	v_lshl_add_u64 v[8:9], v[10:11], 0, v[8:9]
	s_cmpk_lt_i32 s28, 0xc0
	s_mov_b32 s28, s12
	s_waitcnt lgkmcnt(0)
	global_store_dwordx4 v[8:9], v[4:7], off
	s_barrier
	s_cbranch_scc0 .LBB0_887
